# attention A+D: staging ds_writes/loads made unconditional and sprinkled one per MFMA gap instead of a burst
# speedup vs baseline: 1.0110x; 1.0110x over previous
; template <int DQK, int KA8, int DV, bool BIAS, bool JOINT>
; DI void attn_core(LAS unsigned char* lds, const bf16_t* Qrow, const bf16_t* KpA, int ldkA, const bf16_t* KpB, int ldkB, const bf16_t* Vp, int ldv,
;                   int qb, int wid, int lane, const float* qng  , f32x16 (&O)[DV / 32]) {
;     ...
;         if (JOINT && kt <= myc) {
;             LAS unsigned char* kb = lds + (kt & 1) * STG; LAS unsigned char* vb = kb + 64 * KROW;
;             const bool far = (kt * 64 + 63 - q0w <= -91);
;             f32x16 S0, S1;
; #pragma unroll
;             for (int i = 0; i < 16; ++i) { S0[i] = 0.f; S1[i] = 0.f; }
; #pragma unroll
;             for (int s = 0; s < DQK / 16; ++s) {
;                 const bf16x8 k0 = *(LAS const bf16x8*)(kb + koff + 32 * s), k1 = *(LAS const bf16x8*)(kb + koff + 32 * KROW + 32 * s);
;                 S0 = mfma32(k0, qf[s], S0); S1 = mfma32(k1, qf[s], S1);
;             }
;             if (BIAS && !far) {
;                 const int rb = kt * 64 - (q0w + l32) + 128;
; #pragma unroll
;                 for (int i = 0; i < 16; ++i) { const int i0 = rb + crow(i, hh); S0[i] += btab[i0 < 0 ? 0 : i0]; S1[i] += btab[i0 + 32 < 0 ? 0 : i0 + 32]; }
;             }
;             if (mnz) {
; #pragma unroll
;                 for (int i = 0; i < 16; ++i) { S0[i] -= m; S1[i] -= m; }
;             }
;             float mx = fmaxf(S0[0], S1[0]);
; #pragma unroll
;             for (int i = 1; i < 16; ++i) mx = fmaxf(mx, fmaxf(S0[i], S1[i]));
;             mx = fmaxf(mx, __shfl_xor(mx, 32));
;             if (__any(mx > 64.f || (kt == 0 && mx < -64.f))) {
;                 const float dm = (mx > 64.f || (kt == 0 && mx < -64.f)) ? mx : 0.f, alpha = __builtin_amdgcn_exp2f(-dm); m += dm; mnz = true;
;                 l *= alpha;
; #pragma unroll
;                 for (int dt = 0; dt < DV / 32; ++dt) O[dt] *= alpha;
; #pragma unroll
;                 for (int i = 0; i < 16; ++i) { S0[i] -= dm; S1[i] -= dm; }
;             }
;             float ps = 0.f;
; #pragma unroll
;             for (int i = 0; i < 16; ++i) { S0[i] = __builtin_amdgcn_exp2f(S0[i]); S1[i] = __builtin_amdgcn_exp2f(S1[i]); ps += S0[i] + S1[i]; }
;             l += ps;
; #pragma unroll
;             for (int half = 0; half < 2; ++half)
; #pragma unroll
;                 for (int s = 0; s < 2; ++s) {
;                     const f32x16& S = half ? S1 : S0;
.Laa_loop:
	s_add_i32 s58, s25, 1
	s_cmp_eq_u32 s24, 0
	s_cbranch_scc1 .Laa_x0_qk
	s_cmp_gt_u32 s24, s58
	s_cbranch_scc1 .Laa_x0_none
	s_cmp_eq_u32 s24, s58
	s_cbranch_scc1 .Laa_x0_pv
	ds_read_b64_tr_b16 v[140:141], v173 offset:38912
	ds_read_b64_tr_b16 v[142:143], v173 offset:41472
	ds_read_b64_tr_b16 v[144:145], v173 offset:38976
	ds_read_b64_tr_b16 v[146:147], v173 offset:41536
	ds_read_b64_tr_b16 v[148:149], v173 offset:39040
	ds_read_b64_tr_b16 v[150:151], v173 offset:41600
	ds_read_b64_tr_b16 v[152:153], v173 offset:39104
	ds_read_b64_tr_b16 v[154:155], v173 offset:41664
	ds_read_b64_tr_b16 v[156:157], v173 offset:44032
	ds_read_b64_tr_b16 v[158:159], v173 offset:46592
	ds_read_b64_tr_b16 v[160:161], v173 offset:44096
	ds_read_b64_tr_b16 v[162:163], v173 offset:46656
	s_waitcnt lgkmcnt(10)
	v_mfma_f32_32x32x16_bf16 v[0:15], v[140:143], v[96:99], v[0:15]
	ds_read_b64_tr_b16 v[164:165], v173 offset:44160
	ds_read_b64_tr_b16 v[166:167], v173 offset:46720
	s_waitcnt lgkmcnt(10)
	v_mfma_f32_32x32x16_bf16 v[16:31], v[144:147], v[96:99], v[16:31]
	s_waitcnt vmcnt(3)
	ds_write_b128 v174, v[128:131] offset:9216
	ds_read_b64_tr_b16 v[168:169], v173 offset:44224
	ds_read_b64_tr_b16 v[170:171], v173 offset:46784
	s_waitcnt lgkmcnt(11)
	v_mfma_f32_32x32x16_bf16 v[32:47], v[148:151], v[96:99], v[32:47]
	ds_write_b128 v175, v[132:135] offset:18432
	ds_read_b64_tr_b16 v[140:141], v173 offset:49152
	ds_read_b64_tr_b16 v[142:143], v173 offset:51712
	s_waitcnt lgkmcnt(12)
	v_mfma_f32_32x32x16_bf16 v[48:63], v[152:155], v[96:99], v[48:63]
	ds_write_b128 v175, v[136:139] offset:28672
	ds_read_b64_tr_b16 v[144:145], v173 offset:49216
	ds_read_b64_tr_b16 v[146:147], v173 offset:51776
	s_waitcnt lgkmcnt(13)
	v_mfma_f32_32x32x16_bf16 v[0:15], v[156:159], v[100:103], v[0:15]
	ds_read_b64_tr_b16 v[148:149], v173 offset:49280
	ds_read_b64_tr_b16 v[150:151], v173 offset:51840
	s_waitcnt lgkmcnt(13)
	v_mfma_f32_32x32x16_bf16 v[16:31], v[160:163], v[100:103], v[16:31]
	ds_read_b64_tr_b16 v[152:153], v173 offset:49344
	ds_read_b64_tr_b16 v[154:155], v173 offset:51904
	s_waitcnt lgkmcnt(13)
	v_mfma_f32_32x32x16_bf16 v[32:47], v[164:167], v[100:103], v[32:47]
	ds_read_b64_tr_b16 v[156:157], v173 offset:54272
	ds_read_b64_tr_b16 v[158:159], v173 offset:56832
	s_waitcnt lgkmcnt(12)
	v_mfma_f32_32x32x16_bf16 v[48:63], v[168:171], v[100:103], v[48:63]
	ds_read_b64_tr_b16 v[160:161], v173 offset:54336
	ds_read_b64_tr_b16 v[162:163], v173 offset:56896
	s_waitcnt lgkmcnt(11)
	v_mfma_f32_32x32x16_bf16 v[0:15], v[140:143], v[104:107], v[0:15]
	ds_read_b64_tr_b16 v[164:165], v173 offset:54400
	ds_read_b64_tr_b16 v[166:167], v173 offset:56960
	s_waitcnt lgkmcnt(10)
	v_mfma_f32_32x32x16_bf16 v[16:31], v[144:147], v[104:107], v[16:31]
	ds_read_b64_tr_b16 v[168:169], v173 offset:54464
	ds_read_b64_tr_b16 v[170:171], v173 offset:57024
	s_waitcnt lgkmcnt(10)
	v_mfma_f32_32x32x16_bf16 v[32:47], v[148:151], v[104:107], v[32:47]
	ds_read_b128 v[140:143], v172 offset:0
	s_waitcnt lgkmcnt(9)
	v_mfma_f32_32x32x16_bf16 v[48:63], v[152:155], v[104:107], v[48:63]
	ds_read_b128 v[144:147], v172 offset:4608
	s_waitcnt lgkmcnt(8)
	v_mfma_f32_32x32x16_bf16 v[0:15], v[156:159], v[108:111], v[0:15]
	ds_read_b128 v[148:151], v172 offset:32
	s_waitcnt lgkmcnt(7)
	v_mfma_f32_32x32x16_bf16 v[16:31], v[160:163], v[108:111], v[16:31]
	ds_read_b128 v[152:155], v172 offset:4640
	s_waitcnt lgkmcnt(6)
	v_mfma_f32_32x32x16_bf16 v[32:47], v[164:167], v[108:111], v[32:47]
	ds_read_b128 v[156:159], v172 offset:64
	s_waitcnt lgkmcnt(5)
	v_mfma_f32_32x32x16_bf16 v[48:63], v[168:171], v[108:111], v[48:63]
	ds_read_b128 v[160:163], v172 offset:4672
	s_waitcnt lgkmcnt(5)
	v_mfma_f32_32x32x16_bf16 v[64:79], v[140:143], v[112:115], 0
	ds_read_b128 v[164:167], v172 offset:96
	s_waitcnt lgkmcnt(5)
	v_mfma_f32_32x32x16_bf16 v[80:95], v[144:147], v[112:115], 0
	ds_read_b128 v[168:171], v172 offset:4704
	s_waitcnt lgkmcnt(5)
	v_mfma_f32_32x32x16_bf16 v[64:79], v[148:151], v[116:119], v[64:79]
	s_waitcnt lgkmcnt(4)
	v_mfma_f32_32x32x16_bf16 v[80:95], v[152:155], v[116:119], v[80:95]
	s_waitcnt lgkmcnt(3)
	v_mfma_f32_32x32x16_bf16 v[64:79], v[156:159], v[120:123], v[64:79]
	s_waitcnt lgkmcnt(2)
	v_mfma_f32_32x32x16_bf16 v[80:95], v[160:163], v[120:123], v[80:95]
	s_waitcnt lgkmcnt(1)
	v_mfma_f32_32x32x16_bf16 v[64:79], v[164:167], v[124:127], v[64:79]
	s_waitcnt lgkmcnt(0)
	v_mfma_f32_32x32x16_bf16 v[80:95], v[168:171], v[124:127], v[80:95]
	s_branch .Laa_x0_end
; #define LAS __attribute__((address_space(3)))
; DI unsigned pk2(float a, float b) { f32x2 v = {a, b}; bf16v2_t r = __builtin_convertvector(v, bf16v2_t); return __builtin_bit_cast(unsigned, r); }
; DI f32x16 mfma32(bf16x8 a, bf16x8 b, f32x16 c) { return __builtin_amdgcn_mfma_f32_32x32x16_bf16(a, b, c, 0, 0, 0); }
; DI s16x4 trread(LAS unsigned char* p) { return __builtin_amdgcn_ds_read_tr16_b64_v4i16((LAS s16x4*)p); }
; DI bf16x8 cat4(s16x4 lo, s16x4 hi) { return __builtin_shufflevector(lo, hi, 0, 1, 2, 3, 4, 5, 6, 7); }
; template <int DQK, int KA8, int DV, bool BIAS, bool JOINT>
; DI void attn_core(LAS unsigned char* lds, const bf16_t* Qrow, const bf16_t* KpA, int ldkA, const bf16_t* KpB, int ldkB, const bf16_t* Vp, int ldv,
;                   int qb, int wid, int lane, const float* qng  , f32x16 (&O)[DV / 32]) {
;     ...
;         if (JOINT && kt <= myc) {
;             LAS unsigned char* kb = lds + (kt & 1) * STG; LAS unsigned char* vb = kb + 64 * KROW;
;             const bool far = (kt * 64 + 63 - q0w <= -91);
;             f32x16 S0, S1;
; #pragma unroll
;             for (int i = 0; i < 16; ++i) { S0[i] = 0.f; S1[i] = 0.f; }
; #pragma unroll
;             for (int s = 0; s < DQK / 16; ++s) {
;                 const bf16x8 k0 = *(LAS const bf16x8*)(kb + koff + 32 * s), k1 = *(LAS const bf16x8*)(kb + koff + 32 * KROW + 32 * s);
;                 S0 = mfma32(k0, qf[s], S0); S1 = mfma32(k1, qf[s], S1);
;             }
;     ...
;             for (int half = 0; half < 2; ++half)
; #pragma unroll
;                 for (int s = 0; s < 2; ++s) {
;                     const f32x16& S = half ? S1 : S0;
;                     u32x4 pw; pw.x = pk2(S[8 * s], S[8 * s + 1]); pw.y = pk2(S[8 * s + 2], S[8 * s + 3]); pw.z = pk2(S[8 * s + 4], S[8 * s + 5]); pw.w = pk2(S[8 * s + 6], S[8 * s + 7]);
;                     const bf16x8 pf = __builtin_bit_cast(bf16x8, pw);
;                     LAS unsigned char* vr = vb + vtr + (32 * half + 16 * s) * VROW;
; #pragma unroll
;                     for (int dt = 0; dt < DV / 32; ++dt) {
;                         const bf16x8 vf = cat4(trread(vr + 64 * dt), trread(vr + 8 * VROW + 64 * dt));
;                         O[dt] = mfma32(vf, pf, O[dt]);
;                     }
.Laa_x0_pv:
	ds_read_b64_tr_b16 v[140:141], v173 offset:38912
	ds_read_b64_tr_b16 v[142:143], v173 offset:41472
	ds_read_b64_tr_b16 v[144:145], v173 offset:38976
	ds_read_b64_tr_b16 v[146:147], v173 offset:41536
	ds_read_b64_tr_b16 v[148:149], v173 offset:39040
	ds_read_b64_tr_b16 v[150:151], v173 offset:41600
	ds_read_b64_tr_b16 v[152:153], v173 offset:39104
	ds_read_b64_tr_b16 v[154:155], v173 offset:41664
	ds_read_b64_tr_b16 v[156:157], v173 offset:44032
	ds_read_b64_tr_b16 v[158:159], v173 offset:46592
	ds_read_b64_tr_b16 v[160:161], v173 offset:44096
	ds_read_b64_tr_b16 v[162:163], v173 offset:46656
	s_waitcnt lgkmcnt(10)
	v_mfma_f32_32x32x16_bf16 v[0:15], v[140:143], v[96:99], v[0:15]
	ds_read_b64_tr_b16 v[164:165], v173 offset:44160
	ds_read_b64_tr_b16 v[166:167], v173 offset:46720
	s_waitcnt lgkmcnt(10)
	v_mfma_f32_32x32x16_bf16 v[16:31], v[144:147], v[96:99], v[16:31]
	s_waitcnt vmcnt(3)
	ds_write_b128 v174, v[128:131] offset:9216
	ds_read_b64_tr_b16 v[168:169], v173 offset:44224
	ds_read_b64_tr_b16 v[170:171], v173 offset:46784
	s_waitcnt lgkmcnt(11)
	v_mfma_f32_32x32x16_bf16 v[32:47], v[148:151], v[96:99], v[32:47]
	ds_write_b128 v175, v[132:135] offset:18432
	ds_read_b64_tr_b16 v[140:141], v173 offset:49152
	ds_read_b64_tr_b16 v[142:143], v173 offset:51712
	s_waitcnt lgkmcnt(12)
	v_mfma_f32_32x32x16_bf16 v[48:63], v[152:155], v[96:99], v[48:63]
	ds_write_b128 v175, v[136:139] offset:28672
	ds_read_b64_tr_b16 v[144:145], v173 offset:49216
	ds_read_b64_tr_b16 v[146:147], v173 offset:51776
	s_waitcnt lgkmcnt(13)
	v_mfma_f32_32x32x16_bf16 v[0:15], v[156:159], v[100:103], v[0:15]
	ds_read_b64_tr_b16 v[148:149], v173 offset:49280
	ds_read_b64_tr_b16 v[150:151], v173 offset:51840
	s_waitcnt lgkmcnt(13)
	v_mfma_f32_32x32x16_bf16 v[16:31], v[160:163], v[100:103], v[16:31]
	ds_read_b64_tr_b16 v[152:153], v173 offset:49344
	ds_read_b64_tr_b16 v[154:155], v173 offset:51904
	s_waitcnt lgkmcnt(13)
	v_mfma_f32_32x32x16_bf16 v[32:47], v[164:167], v[100:103], v[32:47]
	ds_read_b64_tr_b16 v[156:157], v173 offset:54272
	ds_read_b64_tr_b16 v[158:159], v173 offset:56832
	s_waitcnt lgkmcnt(12)
	v_mfma_f32_32x32x16_bf16 v[48:63], v[168:171], v[100:103], v[48:63]
	ds_read_b64_tr_b16 v[160:161], v173 offset:54336
	ds_read_b64_tr_b16 v[162:163], v173 offset:56896
	s_waitcnt lgkmcnt(11)
	v_mfma_f32_32x32x16_bf16 v[0:15], v[140:143], v[104:107], v[0:15]
	ds_read_b64_tr_b16 v[164:165], v173 offset:54400
	ds_read_b64_tr_b16 v[166:167], v173 offset:56960
	s_waitcnt lgkmcnt(10)
	v_mfma_f32_32x32x16_bf16 v[16:31], v[144:147], v[104:107], v[16:31]
	ds_read_b64_tr_b16 v[168:169], v173 offset:54464
	ds_read_b64_tr_b16 v[170:171], v173 offset:57024
	s_waitcnt lgkmcnt(10)
	v_mfma_f32_32x32x16_bf16 v[32:47], v[148:151], v[104:107], v[32:47]
	s_waitcnt lgkmcnt(8)
	v_mfma_f32_32x32x16_bf16 v[48:63], v[152:155], v[104:107], v[48:63]
	s_waitcnt lgkmcnt(6)
	v_mfma_f32_32x32x16_bf16 v[0:15], v[156:159], v[108:111], v[0:15]
	s_waitcnt lgkmcnt(4)
	v_mfma_f32_32x32x16_bf16 v[16:31], v[160:163], v[108:111], v[16:31]
	s_waitcnt lgkmcnt(2)
	v_mfma_f32_32x32x16_bf16 v[32:47], v[164:167], v[108:111], v[32:47]
	s_waitcnt lgkmcnt(0)
	v_mfma_f32_32x32x16_bf16 v[48:63], v[168:171], v[108:111], v[48:63]
	s_branch .Laa_x0_end
.Laa_x0_qk:
	ds_read_b128 v[140:143], v172 offset:0
	ds_read_b128 v[144:147], v172 offset:4608
	ds_read_b128 v[148:151], v172 offset:32
	ds_read_b128 v[152:155], v172 offset:4640
	ds_read_b128 v[156:159], v172 offset:64
	ds_read_b128 v[160:163], v172 offset:4672
	s_waitcnt lgkmcnt(5)
	v_mfma_f32_32x32x16_bf16 v[64:79], v[140:143], v[112:115], 0
	ds_read_b128 v[164:167], v172 offset:96
	s_waitcnt lgkmcnt(5)
	v_mfma_f32_32x32x16_bf16 v[80:95], v[144:147], v[112:115], 0
	s_waitcnt vmcnt(3)
	ds_write_b128 v174, v[128:131] offset:9216
	ds_read_b128 v[168:171], v172 offset:4704
	s_waitcnt lgkmcnt(6)
	v_mfma_f32_32x32x16_bf16 v[64:79], v[148:151], v[116:119], v[64:79]
	ds_write_b128 v175, v[132:135] offset:18432
	s_waitcnt lgkmcnt(6)
	v_mfma_f32_32x32x16_bf16 v[80:95], v[152:155], v[116:119], v[80:95]
	ds_write_b128 v175, v[136:139] offset:28672
	s_waitcnt lgkmcnt(6)
	v_mfma_f32_32x32x16_bf16 v[64:79], v[156:159], v[120:123], v[64:79]
	s_waitcnt lgkmcnt(5)
	v_mfma_f32_32x32x16_bf16 v[80:95], v[160:163], v[120:123], v[80:95]
	s_waitcnt lgkmcnt(4)
	v_mfma_f32_32x32x16_bf16 v[64:79], v[164:167], v[124:127], v[64:79]
	s_waitcnt lgkmcnt(2)
	v_mfma_f32_32x32x16_bf16 v[80:95], v[168:171], v[124:127], v[80:95]
	s_branch .Laa_x0_end
.Laa_x0_none:
	s_waitcnt vmcnt(3)
	ds_write_b128 v174, v[128:131] offset:9216
	ds_write_b128 v175, v[132:135] offset:18432
	ds_write_b128 v175, v[136:139] offset:28672
; DI int crow(int i, int hh) { return (i & 3) + 8 * (i >> 2) + 4 * hh; }
; template <int DQK, int KA8, int DV, bool BIAS, bool JOINT>
; DI void attn_core(LAS unsigned char* lds, const bf16_t* Qrow, const bf16_t* KpA, int ldkA, const bf16_t* KpB, int ldkB, const bf16_t* Vp, int ldv,
;                   int qb, int wid, int lane, const float* qng  , f32x16 (&O)[DV / 32]) {
;     ...
;     auto gload = [&](int kt) {
; #pragma unroll
;         for (int i = 0; i < NL; ++i) { const int c = tid + i * 512;
;             if (i * 512 < NKC) { const int row = c / KC, cc = c % KC;
;                 const bf16_t* src = (cc < KA8) ? KpA + (size_t)(kt * 64 + row) * ldkA + cc * 8 : KpB + (size_t)(kt * 64 + row) * ldkB + (cc - KA8) * 8;
;                 stg[i] = *(const u32x4*)src; }
;             else { const int c2 = c - NKC, row = c2 / VC, cc = c2 % VC; stg[i] = *(const u32x4*)(Vp + (size_t)(kt * 64 + row) * ldv + cc * 8); } }
;     };
;     ...
;             if (BIAS && !far) {
;                 const int rb = kt * 64 - (q0w + l32) + 128;
; #pragma unroll
;                 for (int i = 0; i < 16; ++i) { const int i0 = rb + crow(i, hh); S0[i] += btab[i0 < 0 ? 0 : i0]; S1[i] += btab[i0 + 32 < 0 ? 0 : i0 + 32]; }
;             }
.Laa_x0_end:
	s_waitcnt lgkmcnt(0)
	s_barrier
	global_load_dwordx4 v[132:135], v177, s[34:35]
	global_load_dwordx4 v[136:139], v182, s[34:35]
	s_add_u32 s34, s34, 0x100000
	s_addc_u32 s35, s35, 0
	global_load_dwordx4 v[128:131], v176, s[30:31]
	s_add_u32 s30, s30, 0x100000
	s_addc_u32 s31, s31, 0
	s_cmp_gt_u32 s24, s25
	s_cbranch_scc1 .Laa_y0_end
	s_nop 15
	s_lshl_b32 s58, s24, 6
	s_add_i32 s60, s58, 154
	s_cmp_gt_i32 s60, s43
	s_cbranch_scc0 .Laa_y0_nobias
	v_add_u32_e32 v186, s58, v203
	v_max_i32_e32 v188, 0xffffffe0, v186
	v_max_i32_e32 v187, 0, v186
	v_lshlrev_b32_e32 v187, 2, v187
	v_lshlrev_b32_e32 v188, 2, v188
	ds_read_b32 v140, v187 offset:59392
	ds_read_b32 v156, v188 offset:59520
	v_add_u32_e32 v189, 1, v186
	v_max_i32_e32 v190, 0xffffffe0, v189
	v_max_i32_e32 v189, 0, v189
	v_lshlrev_b32_e32 v189, 2, v189
	v_lshlrev_b32_e32 v190, 2, v190
	ds_read_b32 v141, v189 offset:59392
	ds_read_b32 v157, v190 offset:59520
	v_add_u32_e32 v193, 2, v186
	v_max_i32_e32 v195, 0xffffffe0, v193
	v_max_i32_e32 v193, 0, v193
	v_lshlrev_b32_e32 v193, 2, v193
	v_lshlrev_b32_e32 v195, 2, v195
	ds_read_b32 v142, v193 offset:59392
	ds_read_b32 v158, v195 offset:59520
	v_add_u32_e32 v196, 3, v186
	v_max_i32_e32 v236, 0xffffffe0, v196
	v_max_i32_e32 v196, 0, v196
	v_lshlrev_b32_e32 v196, 2, v196
	v_lshlrev_b32_e32 v236, 2, v236
	ds_read_b32 v143, v196 offset:59392
	ds_read_b32 v159, v236 offset:59520
	s_waitcnt lgkmcnt(0)
	v_add_f32_e32 v64, v64, v140
	v_add_f32_e32 v80, v80, v156
	v_add_f32_e32 v65, v65, v141
	v_add_f32_e32 v81, v81, v157
	v_add_f32_e32 v66, v66, v142
	v_add_f32_e32 v82, v82, v158
	v_add_f32_e32 v67, v67, v143
	v_add_f32_e32 v83, v83, v159
	v_add_u32_e32 v187, 8, v186
	v_max_i32_e32 v188, 0xffffffe0, v187
	v_max_i32_e32 v187, 0, v187
	v_lshlrev_b32_e32 v187, 2, v187
	v_lshlrev_b32_e32 v188, 2, v188
	ds_read_b32 v144, v187 offset:59392
	ds_read_b32 v160, v188 offset:59520
	v_add_u32_e32 v189, 9, v186
	v_max_i32_e32 v190, 0xffffffe0, v189
	v_max_i32_e32 v189, 0, v189
	v_lshlrev_b32_e32 v189, 2, v189
	v_lshlrev_b32_e32 v190, 2, v190
	ds_read_b32 v145, v189 offset:59392
	ds_read_b32 v161, v190 offset:59520
	v_add_u32_e32 v193, 10, v186
	v_max_i32_e32 v195, 0xffffffe0, v193
	v_max_i32_e32 v193, 0, v193
	v_lshlrev_b32_e32 v193, 2, v193
	v_lshlrev_b32_e32 v195, 2, v195
	ds_read_b32 v146, v193 offset:59392
	ds_read_b32 v162, v195 offset:59520
	v_add_u32_e32 v196, 11, v186
	v_max_i32_e32 v236, 0xffffffe0, v196
	v_max_i32_e32 v196, 0, v196
	v_lshlrev_b32_e32 v196, 2, v196
	v_lshlrev_b32_e32 v236, 2, v236
	ds_read_b32 v147, v196 offset:59392
	ds_read_b32 v163, v236 offset:59520
	s_waitcnt lgkmcnt(0)
	v_add_f32_e32 v68, v68, v144
	v_add_f32_e32 v84, v84, v160
	v_add_f32_e32 v69, v69, v145
	v_add_f32_e32 v85, v85, v161
	v_add_f32_e32 v70, v70, v146
	v_add_f32_e32 v86, v86, v162
	v_add_f32_e32 v71, v71, v147
	v_add_f32_e32 v87, v87, v163
	v_add_u32_e32 v187, 16, v186
	v_max_i32_e32 v188, 0xffffffe0, v187
	v_max_i32_e32 v187, 0, v187
	v_lshlrev_b32_e32 v187, 2, v187
	v_lshlrev_b32_e32 v188, 2, v188
	ds_read_b32 v148, v187 offset:59392
	ds_read_b32 v164, v188 offset:59520
	v_add_u32_e32 v189, 17, v186
	v_max_i32_e32 v190, 0xffffffe0, v189
	v_max_i32_e32 v189, 0, v189
	v_lshlrev_b32_e32 v189, 2, v189
	v_lshlrev_b32_e32 v190, 2, v190
	ds_read_b32 v149, v189 offset:59392
	ds_read_b32 v165, v190 offset:59520
	v_add_u32_e32 v193, 18, v186
	v_max_i32_e32 v195, 0xffffffe0, v193
	v_max_i32_e32 v193, 0, v193
	v_lshlrev_b32_e32 v193, 2, v193
	v_lshlrev_b32_e32 v195, 2, v195
	ds_read_b32 v150, v193 offset:59392
	ds_read_b32 v166, v195 offset:59520
	v_add_u32_e32 v196, 19, v186
	v_max_i32_e32 v236, 0xffffffe0, v196
	v_max_i32_e32 v196, 0, v196
	v_lshlrev_b32_e32 v196, 2, v196
	v_lshlrev_b32_e32 v236, 2, v236
	ds_read_b32 v151, v196 offset:59392
	ds_read_b32 v167, v236 offset:59520
	s_waitcnt lgkmcnt(0)
	v_add_f32_e32 v72, v72, v148
	v_add_f32_e32 v88, v88, v164
	v_add_f32_e32 v73, v73, v149
	v_add_f32_e32 v89, v89, v165
	v_add_f32_e32 v74, v74, v150
	v_add_f32_e32 v90, v90, v166
	v_add_f32_e32 v75, v75, v151
	v_add_f32_e32 v91, v91, v167
	v_add_u32_e32 v187, 24, v186
	v_max_i32_e32 v188, 0xffffffe0, v187
	v_max_i32_e32 v187, 0, v187
	v_lshlrev_b32_e32 v187, 2, v187
	v_lshlrev_b32_e32 v188, 2, v188
	ds_read_b32 v152, v187 offset:59392
	ds_read_b32 v168, v188 offset:59520
	v_add_u32_e32 v189, 25, v186
	v_max_i32_e32 v190, 0xffffffe0, v189
	v_max_i32_e32 v189, 0, v189
	v_lshlrev_b32_e32 v189, 2, v189
	v_lshlrev_b32_e32 v190, 2, v190
	ds_read_b32 v153, v189 offset:59392
	ds_read_b32 v169, v190 offset:59520
	v_add_u32_e32 v193, 26, v186
	v_max_i32_e32 v195, 0xffffffe0, v193
	v_max_i32_e32 v193, 0, v193
	v_lshlrev_b32_e32 v193, 2, v193
	v_lshlrev_b32_e32 v195, 2, v195
	ds_read_b32 v154, v193 offset:59392
	ds_read_b32 v170, v195 offset:59520
	v_add_u32_e32 v196, 27, v186
	v_max_i32_e32 v236, 0xffffffe0, v196
	v_max_i32_e32 v196, 0, v196
	v_lshlrev_b32_e32 v196, 2, v196
	v_lshlrev_b32_e32 v236, 2, v236
	ds_read_b32 v155, v196 offset:59392
	ds_read_b32 v171, v236 offset:59520
	s_waitcnt lgkmcnt(0)
	v_add_f32_e32 v76, v76, v152
	v_add_f32_e32 v92, v92, v168
	v_add_f32_e32 v77, v77, v153
	v_add_f32_e32 v93, v93, v169
	v_add_f32_e32 v78, v78, v154
	v_add_f32_e32 v94, v94, v170
	v_add_f32_e32 v79, v79, v155
	v_add_f32_e32 v95, v95, v171

; template <int DQK, int KA8, int DV, bool BIAS, bool JOINT>
; DI void attn_core(LAS unsigned char* lds, const bf16_t* Qrow, const bf16_t* KpA, int ldkA, const bf16_t* KpB, int ldkB, const bf16_t* Vp, int ldv,
;                   int qb, int wid, int lane, const float* qng  , f32x16 (&O)[DV / 32]) {
;     ...
;         if (JOINT && kt <= myc) {
;             LAS unsigned char* kb = lds + (kt & 1) * STG; LAS unsigned char* vb = kb + 64 * KROW;
;             const bool far = (kt * 64 + 63 - q0w <= -91);
;             f32x16 S0, S1;
; #pragma unroll
;             for (int i = 0; i < 16; ++i) { S0[i] = 0.f; S1[i] = 0.f; }
; #pragma unroll
;             for (int s = 0; s < DQK / 16; ++s) {
;                 const bf16x8 k0 = *(LAS const bf16x8*)(kb + koff + 32 * s), k1 = *(LAS const bf16x8*)(kb + koff + 32 * KROW + 32 * s);
;                 S0 = mfma32(k0, qf[s], S0); S1 = mfma32(k1, qf[s], S1);
;             }
;             if (BIAS && !far) {
;                 const int rb = kt * 64 - (q0w + l32) + 128;
; #pragma unroll
;                 for (int i = 0; i < 16; ++i) { const int i0 = rb + crow(i, hh); S0[i] += btab[i0 < 0 ? 0 : i0]; S1[i] += btab[i0 + 32 < 0 ? 0 : i0 + 32]; }
;             }
;             if (mnz) {
; #pragma unroll
;                 for (int i = 0; i < 16; ++i) { S0[i] -= m; S1[i] -= m; }
;             }
;             float mx = fmaxf(S0[0], S1[0]);
; #pragma unroll
;             for (int i = 1; i < 16; ++i) mx = fmaxf(mx, fmaxf(S0[i], S1[i]));
;             mx = fmaxf(mx, __shfl_xor(mx, 32));
;             if (__any(mx > 64.f || (kt == 0 && mx < -64.f))) {
;                 const float dm = (mx > 64.f || (kt == 0 && mx < -64.f)) ? mx : 0.f, alpha = __builtin_amdgcn_exp2f(-dm); m += dm; mnz = true;
;                 l *= alpha;
; #pragma unroll
;                 for (int dt = 0; dt < DV / 32; ++dt) O[dt] *= alpha;
; #pragma unroll
;                 for (int i = 0; i < 16; ++i) { S0[i] -= dm; S1[i] -= dm; }
;             }
;             float ps = 0.f;
; #pragma unroll
;             for (int i = 0; i < 16; ++i) { S0[i] = __builtin_amdgcn_exp2f(S0[i]); S1[i] = __builtin_amdgcn_exp2f(S1[i]); ps += S0[i] + S1[i]; }
;             l += ps;
; #pragma unroll
;             for (int half = 0; half < 2; ++half)
; #pragma unroll
;                 for (int s = 0; s < 2; ++s) {
;                     const f32x16& S = half ? S1 : S0;
.Laa_y0_end:
	s_barrier
	s_add_i32 s59, s24, 1
	s_add_i32 s58, s25, 1
	s_cmp_gt_u32 s59, s58
	s_cbranch_scc1 .Laa_x1_none
	s_cmp_eq_u32 s59, s58
	s_cbranch_scc1 .Laa_x1_pv
	ds_read_b64_tr_b16 v[140:141], v173 offset:18432
	ds_read_b64_tr_b16 v[142:143], v173 offset:20992
	ds_read_b64_tr_b16 v[144:145], v173 offset:18496
	ds_read_b64_tr_b16 v[146:147], v173 offset:21056
	ds_read_b64_tr_b16 v[148:149], v173 offset:18560
	ds_read_b64_tr_b16 v[150:151], v173 offset:21120
	ds_read_b64_tr_b16 v[152:153], v173 offset:18624
	ds_read_b64_tr_b16 v[154:155], v173 offset:21184
	ds_read_b64_tr_b16 v[156:157], v173 offset:23552
	ds_read_b64_tr_b16 v[158:159], v173 offset:26112
	ds_read_b64_tr_b16 v[160:161], v173 offset:23616
	ds_read_b64_tr_b16 v[162:163], v173 offset:26176
	s_waitcnt lgkmcnt(10)
	v_mfma_f32_32x32x16_bf16 v[0:15], v[140:143], v[96:99], v[0:15]
	ds_read_b64_tr_b16 v[164:165], v173 offset:23680
	ds_read_b64_tr_b16 v[166:167], v173 offset:26240
	s_waitcnt lgkmcnt(10)
	v_mfma_f32_32x32x16_bf16 v[16:31], v[144:147], v[96:99], v[16:31]
	s_waitcnt vmcnt(3)
	ds_write_b128 v174, v[204:207] offset:0
	ds_read_b64_tr_b16 v[168:169], v173 offset:23744
	ds_read_b64_tr_b16 v[170:171], v173 offset:26304
	s_waitcnt lgkmcnt(11)
	v_mfma_f32_32x32x16_bf16 v[32:47], v[148:151], v[96:99], v[32:47]
	ds_write_b128 v175, v[208:211] offset:38912
	ds_read_b64_tr_b16 v[140:141], v173 offset:28672
	ds_read_b64_tr_b16 v[142:143], v173 offset:31232
	s_waitcnt lgkmcnt(12)
	v_mfma_f32_32x32x16_bf16 v[48:63], v[152:155], v[96:99], v[48:63]
	ds_write_b128 v175, v[212:215] offset:49152
	ds_read_b64_tr_b16 v[144:145], v173 offset:28736
	ds_read_b64_tr_b16 v[146:147], v173 offset:31296
	s_waitcnt lgkmcnt(13)
	v_mfma_f32_32x32x16_bf16 v[0:15], v[156:159], v[100:103], v[0:15]
	ds_read_b64_tr_b16 v[148:149], v173 offset:28800
	ds_read_b64_tr_b16 v[150:151], v173 offset:31360
	s_waitcnt lgkmcnt(13)
	v_mfma_f32_32x32x16_bf16 v[16:31], v[160:163], v[100:103], v[16:31]
	ds_read_b64_tr_b16 v[152:153], v173 offset:28864
	ds_read_b64_tr_b16 v[154:155], v173 offset:31424
	s_waitcnt lgkmcnt(13)
	v_mfma_f32_32x32x16_bf16 v[32:47], v[164:167], v[100:103], v[32:47]
	ds_read_b64_tr_b16 v[156:157], v173 offset:33792
	ds_read_b64_tr_b16 v[158:159], v173 offset:36352
	s_waitcnt lgkmcnt(12)
	v_mfma_f32_32x32x16_bf16 v[48:63], v[168:171], v[100:103], v[48:63]
	ds_read_b64_tr_b16 v[160:161], v173 offset:33856
	ds_read_b64_tr_b16 v[162:163], v173 offset:36416
	s_waitcnt lgkmcnt(11)
	v_mfma_f32_32x32x16_bf16 v[0:15], v[140:143], v[104:107], v[0:15]
	ds_read_b64_tr_b16 v[164:165], v173 offset:33920
	ds_read_b64_tr_b16 v[166:167], v173 offset:36480
	s_waitcnt lgkmcnt(10)
	v_mfma_f32_32x32x16_bf16 v[16:31], v[144:147], v[104:107], v[16:31]
	ds_read_b64_tr_b16 v[168:169], v173 offset:33984
	ds_read_b64_tr_b16 v[170:171], v173 offset:36544
	s_waitcnt lgkmcnt(10)
	v_mfma_f32_32x32x16_bf16 v[32:47], v[148:151], v[104:107], v[32:47]
	ds_read_b128 v[140:143], v172 offset:9216
	s_waitcnt lgkmcnt(9)
	v_mfma_f32_32x32x16_bf16 v[48:63], v[152:155], v[104:107], v[48:63]
	ds_read_b128 v[144:147], v172 offset:13824
	s_waitcnt lgkmcnt(8)
	v_mfma_f32_32x32x16_bf16 v[0:15], v[156:159], v[108:111], v[0:15]
	ds_read_b128 v[148:151], v172 offset:9248
	s_waitcnt lgkmcnt(7)
	v_mfma_f32_32x32x16_bf16 v[16:31], v[160:163], v[108:111], v[16:31]
	ds_read_b128 v[152:155], v172 offset:13856
	s_waitcnt lgkmcnt(6)
	v_mfma_f32_32x32x16_bf16 v[32:47], v[164:167], v[108:111], v[32:47]
	ds_read_b128 v[156:159], v172 offset:9280
	s_waitcnt lgkmcnt(5)
	v_mfma_f32_32x32x16_bf16 v[48:63], v[168:171], v[108:111], v[48:63]
	ds_read_b128 v[160:163], v172 offset:13888
	s_waitcnt lgkmcnt(5)
	v_mfma_f32_32x32x16_bf16 v[64:79], v[140:143], v[112:115], 0
	ds_read_b128 v[164:167], v172 offset:9312
	s_waitcnt lgkmcnt(5)
	v_mfma_f32_32x32x16_bf16 v[80:95], v[144:147], v[112:115], 0
	ds_read_b128 v[168:171], v172 offset:13920
	s_waitcnt lgkmcnt(5)
	v_mfma_f32_32x32x16_bf16 v[64:79], v[148:151], v[116:119], v[64:79]
	s_waitcnt lgkmcnt(4)
	v_mfma_f32_32x32x16_bf16 v[80:95], v[152:155], v[116:119], v[80:95]
	s_waitcnt lgkmcnt(3)
	v_mfma_f32_32x32x16_bf16 v[64:79], v[156:159], v[120:123], v[64:79]
	s_waitcnt lgkmcnt(2)
	v_mfma_f32_32x32x16_bf16 v[80:95], v[160:163], v[120:123], v[80:95]
	s_waitcnt lgkmcnt(1)
	v_mfma_f32_32x32x16_bf16 v[64:79], v[164:167], v[124:127], v[64:79]
	s_waitcnt lgkmcnt(0)
	v_mfma_f32_32x32x16_bf16 v[80:95], v[168:171], v[124:127], v[80:95]
	s_branch .Laa_x1_end
; #define LAS __attribute__((address_space(3)))
; DI unsigned pk2(float a, float b) { f32x2 v = {a, b}; bf16v2_t r = __builtin_convertvector(v, bf16v2_t); return __builtin_bit_cast(unsigned, r); }
; DI f32x16 mfma32(bf16x8 a, bf16x8 b, f32x16 c) { return __builtin_amdgcn_mfma_f32_32x32x16_bf16(a, b, c, 0, 0, 0); }
; DI s16x4 trread(LAS unsigned char* p) { return __builtin_amdgcn_ds_read_tr16_b64_v4i16((LAS s16x4*)p); }
; DI bf16x8 cat4(s16x4 lo, s16x4 hi) { return __builtin_shufflevector(lo, hi, 0, 1, 2, 3, 4, 5, 6, 7); }
; template <int DQK, int KA8, int DV, bool BIAS, bool JOINT>
; DI void attn_core(LAS unsigned char* lds, const bf16_t* Qrow, const bf16_t* KpA, int ldkA, const bf16_t* KpB, int ldkB, const bf16_t* Vp, int ldv,
;                   int qb, int wid, int lane, const float* qng  , f32x16 (&O)[DV / 32]) {
;     ...
;             for (int half = 0; half < 2; ++half)
; #pragma unroll
;                 for (int s = 0; s < 2; ++s) {
;                     const f32x16& S = half ? S1 : S0;
;                     u32x4 pw; pw.x = pk2(S[8 * s], S[8 * s + 1]); pw.y = pk2(S[8 * s + 2], S[8 * s + 3]); pw.z = pk2(S[8 * s + 4], S[8 * s + 5]); pw.w = pk2(S[8 * s + 6], S[8 * s + 7]);
;                     const bf16x8 pf = __builtin_bit_cast(bf16x8, pw);
;                     LAS unsigned char* vr = vb + vtr + (32 * half + 16 * s) * VROW;
; #pragma unroll
;                     for (int dt = 0; dt < DV / 32; ++dt) {
;                         const bf16x8 vf = cat4(trread(vr + 64 * dt), trread(vr + 8 * VROW + 64 * dt));
;                         O[dt] = mfma32(vf, pf, O[dt]);
;                     }
.Laa_x1_pv:
	ds_read_b64_tr_b16 v[140:141], v173 offset:18432
	ds_read_b64_tr_b16 v[142:143], v173 offset:20992
	ds_read_b64_tr_b16 v[144:145], v173 offset:18496
	ds_read_b64_tr_b16 v[146:147], v173 offset:21056
	ds_read_b64_tr_b16 v[148:149], v173 offset:18560
	ds_read_b64_tr_b16 v[150:151], v173 offset:21120
	ds_read_b64_tr_b16 v[152:153], v173 offset:18624
	ds_read_b64_tr_b16 v[154:155], v173 offset:21184
	ds_read_b64_tr_b16 v[156:157], v173 offset:23552
	ds_read_b64_tr_b16 v[158:159], v173 offset:26112
	ds_read_b64_tr_b16 v[160:161], v173 offset:23616
	ds_read_b64_tr_b16 v[162:163], v173 offset:26176
	s_waitcnt lgkmcnt(10)
	v_mfma_f32_32x32x16_bf16 v[0:15], v[140:143], v[96:99], v[0:15]
	ds_read_b64_tr_b16 v[164:165], v173 offset:23680
	ds_read_b64_tr_b16 v[166:167], v173 offset:26240
	s_waitcnt lgkmcnt(10)
	v_mfma_f32_32x32x16_bf16 v[16:31], v[144:147], v[96:99], v[16:31]
	s_waitcnt vmcnt(3)
	ds_write_b128 v174, v[204:207] offset:0
	ds_read_b64_tr_b16 v[168:169], v173 offset:23744
	ds_read_b64_tr_b16 v[170:171], v173 offset:26304
	s_waitcnt lgkmcnt(11)
	v_mfma_f32_32x32x16_bf16 v[32:47], v[148:151], v[96:99], v[32:47]
	ds_write_b128 v175, v[208:211] offset:38912
	ds_read_b64_tr_b16 v[140:141], v173 offset:28672
	ds_read_b64_tr_b16 v[142:143], v173 offset:31232
	s_waitcnt lgkmcnt(12)
	v_mfma_f32_32x32x16_bf16 v[48:63], v[152:155], v[96:99], v[48:63]
	ds_write_b128 v175, v[212:215] offset:49152
	ds_read_b64_tr_b16 v[144:145], v173 offset:28736
	ds_read_b64_tr_b16 v[146:147], v173 offset:31296
	s_waitcnt lgkmcnt(13)
	v_mfma_f32_32x32x16_bf16 v[0:15], v[156:159], v[100:103], v[0:15]
	ds_read_b64_tr_b16 v[148:149], v173 offset:28800
	ds_read_b64_tr_b16 v[150:151], v173 offset:31360
	s_waitcnt lgkmcnt(13)
	v_mfma_f32_32x32x16_bf16 v[16:31], v[160:163], v[100:103], v[16:31]
	ds_read_b64_tr_b16 v[152:153], v173 offset:28864
	ds_read_b64_tr_b16 v[154:155], v173 offset:31424
	s_waitcnt lgkmcnt(13)
	v_mfma_f32_32x32x16_bf16 v[32:47], v[164:167], v[100:103], v[32:47]
	ds_read_b64_tr_b16 v[156:157], v173 offset:33792
	ds_read_b64_tr_b16 v[158:159], v173 offset:36352
	s_waitcnt lgkmcnt(12)
	v_mfma_f32_32x32x16_bf16 v[48:63], v[168:171], v[100:103], v[48:63]
	ds_read_b64_tr_b16 v[160:161], v173 offset:33856
	ds_read_b64_tr_b16 v[162:163], v173 offset:36416
	s_waitcnt lgkmcnt(11)
	v_mfma_f32_32x32x16_bf16 v[0:15], v[140:143], v[104:107], v[0:15]
	ds_read_b64_tr_b16 v[164:165], v173 offset:33920
	ds_read_b64_tr_b16 v[166:167], v173 offset:36480
	s_waitcnt lgkmcnt(10)
	v_mfma_f32_32x32x16_bf16 v[16:31], v[144:147], v[104:107], v[16:31]
	ds_read_b64_tr_b16 v[168:169], v173 offset:33984
	ds_read_b64_tr_b16 v[170:171], v173 offset:36544
	s_waitcnt lgkmcnt(10)
	v_mfma_f32_32x32x16_bf16 v[32:47], v[148:151], v[104:107], v[32:47]
	s_waitcnt lgkmcnt(8)
	v_mfma_f32_32x32x16_bf16 v[48:63], v[152:155], v[104:107], v[48:63]
	s_waitcnt lgkmcnt(6)
	v_mfma_f32_32x32x16_bf16 v[0:15], v[156:159], v[108:111], v[0:15]
	s_waitcnt lgkmcnt(4)
	v_mfma_f32_32x32x16_bf16 v[16:31], v[160:163], v[108:111], v[16:31]
	s_waitcnt lgkmcnt(2)
	v_mfma_f32_32x32x16_bf16 v[32:47], v[164:167], v[108:111], v[32:47]
	s_waitcnt lgkmcnt(0)
	v_mfma_f32_32x32x16_bf16 v[48:63], v[168:171], v[108:111], v[48:63]
	s_branch .Laa_x1_end
.Laa_x1_none:
	s_waitcnt vmcnt(3)
	ds_write_b128 v174, v[204:207] offset:0
	ds_write_b128 v175, v[208:211] offset:38912
	ds_write_b128 v175, v[212:215] offset:49152
; DI int crow(int i, int hh) { return (i & 3) + 8 * (i >> 2) + 4 * hh; }
; template <int DQK, int KA8, int DV, bool BIAS, bool JOINT>
; DI void attn_core(LAS unsigned char* lds, const bf16_t* Qrow, const bf16_t* KpA, int ldkA, const bf16_t* KpB, int ldkB, const bf16_t* Vp, int ldv,
;                   int qb, int wid, int lane, const float* qng  , f32x16 (&O)[DV / 32]) {
;     ...
;     auto gload = [&](int kt) {
; #pragma unroll
;         for (int i = 0; i < NL; ++i) { const int c = tid + i * 512;
;             if (i * 512 < NKC) { const int row = c / KC, cc = c % KC;
;                 const bf16_t* src = (cc < KA8) ? KpA + (size_t)(kt * 64 + row) * ldkA + cc * 8 : KpB + (size_t)(kt * 64 + row) * ldkB + (cc - KA8) * 8;
;                 stg[i] = *(const u32x4*)src; }
;             else { const int c2 = c - NKC, row = c2 / VC, cc = c2 % VC; stg[i] = *(const u32x4*)(Vp + (size_t)(kt * 64 + row) * ldv + cc * 8); } }
;     };
;     ...
;             if (BIAS && !far) {
;                 const int rb = kt * 64 - (q0w + l32) + 128;
; #pragma unroll
;                 for (int i = 0; i < 16; ++i) { const int i0 = rb + crow(i, hh); S0[i] += btab[i0 < 0 ? 0 : i0]; S1[i] += btab[i0 + 32 < 0 ? 0 : i0 + 32]; }
;             }
.Laa_x1_end:
	s_waitcnt lgkmcnt(0)
	s_barrier
	global_load_dwordx4 v[208:211], v177, s[34:35]
	global_load_dwordx4 v[212:215], v182, s[34:35]
	s_add_u32 s34, s34, 0x100000
	s_addc_u32 s35, s35, 0
	global_load_dwordx4 v[204:207], v176, s[30:31]
	s_add_u32 s30, s30, 0x100000
	s_addc_u32 s31, s31, 0
	s_cmp_gt_u32 s59, s25
	s_cbranch_scc1 .Laa_y1_end
	s_nop 15
	s_lshl_b32 s58, s59, 6
	s_add_i32 s60, s58, 154
	s_cmp_gt_i32 s60, s43
	s_cbranch_scc0 .Laa_y1_nobias
	v_add_u32_e32 v186, s58, v203
	v_max_i32_e32 v188, 0xffffffe0, v186
	v_max_i32_e32 v187, 0, v186
	v_lshlrev_b32_e32 v187, 2, v187
	v_lshlrev_b32_e32 v188, 2, v188
	ds_read_b32 v140, v187 offset:59392
	ds_read_b32 v156, v188 offset:59520
	v_add_u32_e32 v189, 1, v186
	v_max_i32_e32 v190, 0xffffffe0, v189
	v_max_i32_e32 v189, 0, v189
	v_lshlrev_b32_e32 v189, 2, v189
	v_lshlrev_b32_e32 v190, 2, v190
	ds_read_b32 v141, v189 offset:59392
	ds_read_b32 v157, v190 offset:59520
	v_add_u32_e32 v193, 2, v186
	v_max_i32_e32 v195, 0xffffffe0, v193
	v_max_i32_e32 v193, 0, v193
	v_lshlrev_b32_e32 v193, 2, v193
	v_lshlrev_b32_e32 v195, 2, v195
	ds_read_b32 v142, v193 offset:59392
	ds_read_b32 v158, v195 offset:59520
	v_add_u32_e32 v196, 3, v186
	v_max_i32_e32 v236, 0xffffffe0, v196
	v_max_i32_e32 v196, 0, v196
	v_lshlrev_b32_e32 v196, 2, v196
	v_lshlrev_b32_e32 v236, 2, v236
	ds_read_b32 v143, v196 offset:59392
	ds_read_b32 v159, v236 offset:59520
	s_waitcnt lgkmcnt(0)
	v_add_f32_e32 v64, v64, v140
	v_add_f32_e32 v80, v80, v156
	v_add_f32_e32 v65, v65, v141
	v_add_f32_e32 v81, v81, v157
	v_add_f32_e32 v66, v66, v142
	v_add_f32_e32 v82, v82, v158
	v_add_f32_e32 v67, v67, v143
	v_add_f32_e32 v83, v83, v159
	v_add_u32_e32 v187, 8, v186
	v_max_i32_e32 v188, 0xffffffe0, v187
	v_max_i32_e32 v187, 0, v187
	v_lshlrev_b32_e32 v187, 2, v187
	v_lshlrev_b32_e32 v188, 2, v188
	ds_read_b32 v144, v187 offset:59392
	ds_read_b32 v160, v188 offset:59520
	v_add_u32_e32 v189, 9, v186
	v_max_i32_e32 v190, 0xffffffe0, v189
	v_max_i32_e32 v189, 0, v189
	v_lshlrev_b32_e32 v189, 2, v189
	v_lshlrev_b32_e32 v190, 2, v190
	ds_read_b32 v145, v189 offset:59392
	ds_read_b32 v161, v190 offset:59520
	v_add_u32_e32 v193, 10, v186
	v_max_i32_e32 v195, 0xffffffe0, v193
	v_max_i32_e32 v193, 0, v193
	v_lshlrev_b32_e32 v193, 2, v193
	v_lshlrev_b32_e32 v195, 2, v195
	ds_read_b32 v146, v193 offset:59392
	ds_read_b32 v162, v195 offset:59520
	v_add_u32_e32 v196, 11, v186
	v_max_i32_e32 v236, 0xffffffe0, v196
	v_max_i32_e32 v196, 0, v196
	v_lshlrev_b32_e32 v196, 2, v196
	v_lshlrev_b32_e32 v236, 2, v236
	ds_read_b32 v147, v196 offset:59392
	ds_read_b32 v163, v236 offset:59520
	s_waitcnt lgkmcnt(0)
	v_add_f32_e32 v68, v68, v144
	v_add_f32_e32 v84, v84, v160
	v_add_f32_e32 v69, v69, v145
	v_add_f32_e32 v85, v85, v161
	v_add_f32_e32 v70, v70, v146
	v_add_f32_e32 v86, v86, v162
	v_add_f32_e32 v71, v71, v147
	v_add_f32_e32 v87, v87, v163
	v_add_u32_e32 v187, 16, v186
	v_max_i32_e32 v188, 0xffffffe0, v187
	v_max_i32_e32 v187, 0, v187
	v_lshlrev_b32_e32 v187, 2, v187
	v_lshlrev_b32_e32 v188, 2, v188
	ds_read_b32 v148, v187 offset:59392
	ds_read_b32 v164, v188 offset:59520
	v_add_u32_e32 v189, 17, v186
	v_max_i32_e32 v190, 0xffffffe0, v189
	v_max_i32_e32 v189, 0, v189
	v_lshlrev_b32_e32 v189, 2, v189
	v_lshlrev_b32_e32 v190, 2, v190
	ds_read_b32 v149, v189 offset:59392
	ds_read_b32 v165, v190 offset:59520
	v_add_u32_e32 v193, 18, v186
	v_max_i32_e32 v195, 0xffffffe0, v193
	v_max_i32_e32 v193, 0, v193
	v_lshlrev_b32_e32 v193, 2, v193
	v_lshlrev_b32_e32 v195, 2, v195
	ds_read_b32 v150, v193 offset:59392
	ds_read_b32 v166, v195 offset:59520
	v_add_u32_e32 v196, 19, v186
	v_max_i32_e32 v236, 0xffffffe0, v196
	v_max_i32_e32 v196, 0, v196
	v_lshlrev_b32_e32 v196, 2, v196
	v_lshlrev_b32_e32 v236, 2, v236
	ds_read_b32 v151, v196 offset:59392
	ds_read_b32 v167, v236 offset:59520
	s_waitcnt lgkmcnt(0)
	v_add_f32_e32 v72, v72, v148
	v_add_f32_e32 v88, v88, v164
	v_add_f32_e32 v73, v73, v149
	v_add_f32_e32 v89, v89, v165
	v_add_f32_e32 v74, v74, v150
	v_add_f32_e32 v90, v90, v166
	v_add_f32_e32 v75, v75, v151
	v_add_f32_e32 v91, v91, v167
	v_add_u32_e32 v187, 24, v186
	v_max_i32_e32 v188, 0xffffffe0, v187
	v_max_i32_e32 v187, 0, v187
	v_lshlrev_b32_e32 v187, 2, v187
	v_lshlrev_b32_e32 v188, 2, v188
	ds_read_b32 v152, v187 offset:59392
	ds_read_b32 v168, v188 offset:59520
	v_add_u32_e32 v189, 25, v186
	v_max_i32_e32 v190, 0xffffffe0, v189
	v_max_i32_e32 v189, 0, v189
	v_lshlrev_b32_e32 v189, 2, v189
	v_lshlrev_b32_e32 v190, 2, v190
	ds_read_b32 v153, v189 offset:59392
	ds_read_b32 v169, v190 offset:59520
	v_add_u32_e32 v193, 26, v186
	v_max_i32_e32 v195, 0xffffffe0, v193
	v_max_i32_e32 v193, 0, v193
	v_lshlrev_b32_e32 v193, 2, v193
	v_lshlrev_b32_e32 v195, 2, v195
	ds_read_b32 v154, v193 offset:59392
	ds_read_b32 v170, v195 offset:59520
	v_add_u32_e32 v196, 27, v186
	v_max_i32_e32 v236, 0xffffffe0, v196
	v_max_i32_e32 v196, 0, v196
	v_lshlrev_b32_e32 v196, 2, v196
	v_lshlrev_b32_e32 v236, 2, v236
	ds_read_b32 v155, v196 offset:59392
	ds_read_b32 v171, v236 offset:59520
	s_waitcnt lgkmcnt(0)
	v_add_f32_e32 v76, v76, v152
	v_add_f32_e32 v92, v92, v168
	v_add_f32_e32 v77, v77, v153
	v_add_f32_e32 v93, v93, v169
	v_add_f32_e32 v78, v78, v154
	v_add_f32_e32 v94, v94, v170
	v_add_f32_e32 v79, v79, v155
	v_add_f32_e32 v95, v95, v171

; template <int DQK, int KA8, int DV, bool BIAS, bool JOINT>
; DI void attn_core(LAS unsigned char* lds, const bf16_t* Qrow, const bf16_t* KpA, int ldkA, const bf16_t* KpB, int ldkB, const bf16_t* Vp, int ldv,
;                   int qb, int wid, int lane, const float* qng  , f32x16 (&O)[DV / 32]) {
;     ...
;     for (int kt = 0; kt < nkt; ++kt) {
;         if (kt + 1 < nkt) gload(kt + 1);
;         if (JOINT && kt <= myc) {
;             LAS unsigned char* kb = lds + (kt & 1) * STG; LAS unsigned char* vb = kb + 64 * KROW;
;             const bool far = (kt * 64 + 63 - q0w <= -91);
;             f32x16 S0, S1;
; #pragma unroll
;             for (int i = 0; i < 16; ++i) { S0[i] = 0.f; S1[i] = 0.f; }
; #pragma unroll
;             for (int s = 0; s < DQK / 16; ++s) {
;                 const bf16x8 k0 = *(LAS const bf16x8*)(kb + koff + 32 * s), k1 = *(LAS const bf16x8*)(kb + koff + 32 * KROW + 32 * s);
;                 S0 = mfma32(k0, qf[s], S0); S1 = mfma32(k1, qf[s], S1);
;             }
;             if (BIAS && !far) {
;                 const int rb = kt * 64 - (q0w + l32) + 128;
; #pragma unroll
;                 for (int i = 0; i < 16; ++i) { const int i0 = rb + crow(i, hh); S0[i] += btab[i0 < 0 ? 0 : i0]; S1[i] += btab[i0 + 32 < 0 ? 0 : i0 + 32]; }
;             }
;             if (mnz) {
; #pragma unroll
;                 for (int i = 0; i < 16; ++i) { S0[i] -= m; S1[i] -= m; }
;             }
;             float mx = fmaxf(S0[0], S1[0]);
; #pragma unroll
;             for (int i = 1; i < 16; ++i) mx = fmaxf(mx, fmaxf(S0[i], S1[i]));
;             mx = fmaxf(mx, __shfl_xor(mx, 32));
;             if (__any(mx > 64.f || (kt == 0 && mx < -64.f))) {
;                 const float dm = (mx > 64.f || (kt == 0 && mx < -64.f)) ? mx : 0.f, alpha = __builtin_amdgcn_exp2f(-dm); m += dm; mnz = true;
;                 l *= alpha;
; #pragma unroll
;                 for (int dt = 0; dt < DV / 32; ++dt) O[dt] *= alpha;
; #pragma unroll
;                 for (int i = 0; i < 16; ++i) { S0[i] -= dm; S1[i] -= dm; }
;             }
;             float ps = 0.f;
; #pragma unroll
;             for (int i = 0; i < 16; ++i) { S0[i] = __builtin_amdgcn_exp2f(S0[i]); S1[i] = __builtin_amdgcn_exp2f(S1[i]); ps += S0[i] + S1[i]; }
;             l += ps;
; #pragma unroll
;             for (int half = 0; half < 2; ++half)
; #pragma unroll
;                 for (int s = 0; s < 2; ++s) {
.Lad_loop:
	s_add_i32 s58, s25, 1
	s_cmp_eq_u32 s24, 0
	s_cbranch_scc1 .Lad_x0_qk
	s_cmp_gt_u32 s24, s58
	s_cbranch_scc1 .Lad_x0_none
	s_cmp_eq_u32 s24, s58
	s_cbranch_scc1 .Lad_x0_pv
	ds_read_b64_tr_b16 v[182:183], v215 offset:20480
	ds_read_b64_tr_b16 v[184:185], v215 offset:23040
	ds_read_b64_tr_b16 v[186:187], v215 offset:20544
	ds_read_b64_tr_b16 v[188:189], v215 offset:23104
	ds_read_b64_tr_b16 v[190:191], v215 offset:20608
	ds_read_b64_tr_b16 v[192:193], v215 offset:23168
	ds_read_b64_tr_b16 v[194:195], v215 offset:20672
	ds_read_b64_tr_b16 v[196:197], v215 offset:23232
	ds_read_b64_tr_b16 v[198:199], v215 offset:25600
	ds_read_b64_tr_b16 v[200:201], v215 offset:28160
	ds_read_b64_tr_b16 v[202:203], v215 offset:25664
	ds_read_b64_tr_b16 v[204:205], v215 offset:28224
	s_waitcnt lgkmcnt(10)
	v_mfma_f32_32x32x16_bf16 v[0:15], v[182:185], v[96:99], v[0:15]
	ds_read_b64_tr_b16 v[206:207], v215 offset:25728
	ds_read_b64_tr_b16 v[208:209], v215 offset:28288
	s_waitcnt lgkmcnt(10)
	v_mfma_f32_32x32x16_bf16 v[16:31], v[186:189], v[96:99], v[16:31]
	ds_read_b64_tr_b16 v[210:211], v215 offset:25792
	ds_read_b64_tr_b16 v[212:213], v215 offset:28352
	s_waitcnt lgkmcnt(10)
	v_mfma_f32_32x32x16_bf16 v[32:47], v[190:193], v[96:99], v[32:47]
	ds_read_b64_tr_b16 v[182:183], v215 offset:30720
	ds_read_b64_tr_b16 v[184:185], v215 offset:33280
	s_waitcnt lgkmcnt(10)
	v_mfma_f32_32x32x16_bf16 v[48:63], v[194:197], v[96:99], v[48:63]
	s_waitcnt vmcnt(0)
	ds_write_b128 v253, v[160:163] offset:0
	ds_read_b64_tr_b16 v[186:187], v215 offset:30784
	ds_read_b64_tr_b16 v[188:189], v215 offset:33344
	s_waitcnt lgkmcnt(11)
	v_mfma_f32_32x32x16_bf16 v[0:15], v[198:201], v[100:103], v[0:15]
	ds_write_b128 v253, v[164:167] offset:12800
	ds_read_b64_tr_b16 v[190:191], v215 offset:30848
	ds_read_b64_tr_b16 v[192:193], v215 offset:33408
	s_waitcnt lgkmcnt(12)
	v_mfma_f32_32x32x16_bf16 v[16:31], v[202:205], v[100:103], v[16:31]
	ds_write_b128 v254, v[168:171] offset:0
	ds_read_b64_tr_b16 v[194:195], v215 offset:30912
	ds_read_b64_tr_b16 v[196:197], v215 offset:33472
	s_waitcnt lgkmcnt(13)
	v_mfma_f32_32x32x16_bf16 v[32:47], v[206:209], v[100:103], v[32:47]
	ds_write_b128 v218, v[172:175] offset:0
	ds_read_b64_tr_b16 v[198:199], v215 offset:35840
	ds_read_b64_tr_b16 v[200:201], v215 offset:38400
	s_waitcnt lgkmcnt(14)
	v_mfma_f32_32x32x16_bf16 v[48:63], v[210:213], v[100:103], v[48:63]
	ds_write_b128 v218, v[176:179] offset:10240
	ds_read_b64_tr_b16 v[202:203], v215 offset:35904
	ds_read_b64_tr_b16 v[204:205], v215 offset:38464
	s_waitcnt lgkmcnt(15)
	v_mfma_f32_32x32x16_bf16 v[0:15], v[182:185], v[104:107], v[0:15]
	global_load_dwordx4 v[172:175], v222, s[34:35]
	ds_read_b64_tr_b16 v[206:207], v215 offset:35968
	ds_read_b64_tr_b16 v[208:209], v215 offset:38528
	s_waitcnt lgkmcnt(14)
	v_mfma_f32_32x32x16_bf16 v[16:31], v[186:189], v[104:107], v[16:31]
	global_load_dwordx4 v[176:179], v223, s[34:35]
	s_add_u32 s34, s34, 0xe0000
	s_addc_u32 s35, s35, 0
	ds_read_b64_tr_b16 v[210:211], v215 offset:36032
	ds_read_b64_tr_b16 v[212:213], v215 offset:38592
	s_waitcnt lgkmcnt(13)
	v_mfma_f32_32x32x16_bf16 v[32:47], v[190:193], v[104:107], v[32:47]
	global_load_dwordx4 v[160:163], v219, s[30:31]
	ds_read_b128 v[182:185], v214 offset:40960
	s_waitcnt lgkmcnt(11)
	v_mfma_f32_32x32x16_bf16 v[48:63], v[194:197], v[104:107], v[48:63]
	global_load_dwordx4 v[164:167], v220, s[30:31]
	s_add_u32 s30, s30, 0xe0000
	s_addc_u32 s31, s31, 0
	ds_read_b128 v[186:189], v214 offset:53760
	s_waitcnt lgkmcnt(9)
	v_mfma_f32_32x32x16_bf16 v[0:15], v[198:201], v[108:111], v[0:15]
	global_load_dwordx4 v[168:171], v221, s[36:37]
	s_add_u32 s36, s36, 0x22000
	s_addc_u32 s37, s37, 0
	ds_read_b128 v[190:193], v214 offset:40992
	s_waitcnt lgkmcnt(7)
	v_mfma_f32_32x32x16_bf16 v[16:31], v[202:205], v[108:111], v[16:31]
	ds_read_b128 v[194:197], v214 offset:53792
	s_waitcnt lgkmcnt(6)
	v_mfma_f32_32x32x16_bf16 v[32:47], v[206:209], v[108:111], v[32:47]
	ds_read_b128 v[198:201], v214 offset:41024
	s_waitcnt lgkmcnt(5)
	v_mfma_f32_32x32x16_bf16 v[48:63], v[210:213], v[108:111], v[48:63]
	ds_read_b128 v[202:205], v214 offset:53824
	s_waitcnt lgkmcnt(5)
	v_mfma_f32_32x32x16_bf16 v[64:79], v[182:185], v[112:115], 0
	ds_read_b128 v[206:209], v214 offset:41056
	s_waitcnt lgkmcnt(5)
	v_mfma_f32_32x32x16_bf16 v[80:95], v[186:189], v[112:115], 0
	ds_read_b128 v[210:213], v214 offset:53856
	s_waitcnt lgkmcnt(5)
	v_mfma_f32_32x32x16_bf16 v[64:79], v[190:193], v[116:119], v[64:79]
	ds_read_b128 v[182:185], v214 offset:41088
	s_waitcnt lgkmcnt(5)
	v_mfma_f32_32x32x16_bf16 v[80:95], v[194:197], v[116:119], v[80:95]
	ds_read_b128 v[186:189], v214 offset:53888
	s_waitcnt lgkmcnt(5)
	v_mfma_f32_32x32x16_bf16 v[64:79], v[198:201], v[120:123], v[64:79]
	ds_read_b128 v[190:193], v214 offset:41120
	s_waitcnt lgkmcnt(5)
	v_mfma_f32_32x32x16_bf16 v[80:95], v[202:205], v[120:123], v[80:95]
	ds_read_b128 v[194:197], v214 offset:53920
	s_waitcnt lgkmcnt(5)
	v_mfma_f32_32x32x16_bf16 v[64:79], v[206:209], v[124:127], v[64:79]
	ds_read_b128 v[198:201], v214 offset:41152
	s_waitcnt lgkmcnt(5)
	v_mfma_f32_32x32x16_bf16 v[80:95], v[210:213], v[124:127], v[80:95]
	ds_read_b128 v[202:205], v214 offset:53952
	s_waitcnt lgkmcnt(5)
	v_mfma_f32_32x32x16_bf16 v[64:79], v[182:185], v[128:131], v[64:79]
	ds_read_b128 v[206:209], v214 offset:41184
	s_waitcnt lgkmcnt(5)
	v_mfma_f32_32x32x16_bf16 v[80:95], v[186:189], v[128:131], v[80:95]
	ds_read_b128 v[210:213], v214 offset:53984
	s_waitcnt lgkmcnt(5)
	v_mfma_f32_32x32x16_bf16 v[64:79], v[190:193], v[132:135], v[64:79]
	ds_read_b128 v[182:185], v214 offset:41216
	s_waitcnt lgkmcnt(5)
; template <int DQK, int KA8, int DV, bool BIAS, bool JOINT>
; DI void attn_core(LAS unsigned char* lds, const bf16_t* Qrow, const bf16_t* KpA, int ldkA, const bf16_t* KpB, int ldkB, const bf16_t* Vp, int ldv,
;                   int qb, int wid, int lane, const float* qng  , f32x16 (&O)[DV / 32]) {
;     ...
;     for (int kt = 0; kt < nkt; ++kt) {
;         if (kt + 1 < nkt) gload(kt + 1);
;         if (JOINT && kt <= myc) {
;             LAS unsigned char* kb = lds + (kt & 1) * STG; LAS unsigned char* vb = kb + 64 * KROW;
;             const bool far = (kt * 64 + 63 - q0w <= -91);
;             f32x16 S0, S1;
; #pragma unroll
;             for (int i = 0; i < 16; ++i) { S0[i] = 0.f; S1[i] = 0.f; }
; #pragma unroll
;             for (int s = 0; s < DQK / 16; ++s) {
;                 const bf16x8 k0 = *(LAS const bf16x8*)(kb + koff + 32 * s), k1 = *(LAS const bf16x8*)(kb + koff + 32 * KROW + 32 * s);
;                 S0 = mfma32(k0, qf[s], S0); S1 = mfma32(k1, qf[s], S1);
;             }
;             if (BIAS && !far) {
;                 const int rb = kt * 64 - (q0w + l32) + 128;
; #pragma unroll
;                 for (int i = 0; i < 16; ++i) { const int i0 = rb + crow(i, hh); S0[i] += btab[i0 < 0 ? 0 : i0]; S1[i] += btab[i0 + 32 < 0 ? 0 : i0 + 32]; }
;             }
;             if (mnz) {
; #pragma unroll
;                 for (int i = 0; i < 16; ++i) { S0[i] -= m; S1[i] -= m; }
;             }
;             float mx = fmaxf(S0[0], S1[0]);
; #pragma unroll
;             for (int i = 1; i < 16; ++i) mx = fmaxf(mx, fmaxf(S0[i], S1[i]));
;             mx = fmaxf(mx, __shfl_xor(mx, 32));
;             if (__any(mx > 64.f || (kt == 0 && mx < -64.f))) {
;                 const float dm = (mx > 64.f || (kt == 0 && mx < -64.f)) ? mx : 0.f, alpha = __builtin_amdgcn_exp2f(-dm); m += dm; mnz = true;
;                 l *= alpha;
; #pragma unroll
;                 for (int dt = 0; dt < DV / 32; ++dt) O[dt] *= alpha;
; #pragma unroll
;                 for (int i = 0; i < 16; ++i) { S0[i] -= dm; S1[i] -= dm; }
;             }
;             float ps = 0.f;
; #pragma unroll
;             for (int i = 0; i < 16; ++i) { S0[i] = __builtin_amdgcn_exp2f(S0[i]); S1[i] = __builtin_amdgcn_exp2f(S1[i]); ps += S0[i] + S1[i]; }
;             l += ps;
; #pragma unroll
;             for (int half = 0; half < 2; ++half)
; #pragma unroll
;                 for (int s = 0; s < 2; ++s) {
	v_mfma_f32_32x32x16_bf16 v[80:95], v[194:197], v[132:135], v[80:95]
	ds_read_b128 v[186:189], v214 offset:54016
	s_waitcnt lgkmcnt(5)
	v_mfma_f32_32x32x16_bf16 v[64:79], v[198:201], v[136:139], v[64:79]
	ds_read_b128 v[190:193], v214 offset:41248
	s_waitcnt lgkmcnt(5)
	v_mfma_f32_32x32x16_bf16 v[80:95], v[202:205], v[136:139], v[80:95]
	ds_read_b128 v[194:197], v214 offset:54048
	s_waitcnt lgkmcnt(5)
	v_mfma_f32_32x32x16_bf16 v[64:79], v[206:209], v[140:143], v[64:79]
	ds_read_b128 v[198:201], v214 offset:41280
	s_waitcnt lgkmcnt(5)
	v_mfma_f32_32x32x16_bf16 v[80:95], v[210:213], v[140:143], v[80:95]
	ds_read_b128 v[202:205], v214 offset:54080
	s_waitcnt lgkmcnt(5)
	v_mfma_f32_32x32x16_bf16 v[64:79], v[182:185], v[144:147], v[64:79]
	ds_read_b128 v[206:209], v214 offset:41312
	s_waitcnt lgkmcnt(5)
	v_mfma_f32_32x32x16_bf16 v[80:95], v[186:189], v[144:147], v[80:95]
	ds_read_b128 v[210:213], v214 offset:54112
	s_waitcnt lgkmcnt(5)
	v_mfma_f32_32x32x16_bf16 v[64:79], v[190:193], v[148:151], v[64:79]
	s_waitcnt lgkmcnt(4)
	v_mfma_f32_32x32x16_bf16 v[80:95], v[194:197], v[148:151], v[80:95]
	s_waitcnt lgkmcnt(3)
	v_mfma_f32_32x32x16_bf16 v[64:79], v[198:201], v[152:155], v[64:79]
	s_waitcnt lgkmcnt(2)
	v_mfma_f32_32x32x16_bf16 v[80:95], v[202:205], v[152:155], v[80:95]
	s_waitcnt lgkmcnt(1)
	v_mfma_f32_32x32x16_bf16 v[64:79], v[206:209], v[156:159], v[64:79]
	s_waitcnt lgkmcnt(0)
	v_mfma_f32_32x32x16_bf16 v[80:95], v[210:213], v[156:159], v[80:95]
	s_branch .Lad_x0_end
.Lad_x0_pv:
	ds_read_b64_tr_b16 v[182:183], v215 offset:20480
	ds_read_b64_tr_b16 v[184:185], v215 offset:23040
	ds_read_b64_tr_b16 v[186:187], v215 offset:20544
	ds_read_b64_tr_b16 v[188:189], v215 offset:23104
	ds_read_b64_tr_b16 v[190:191], v215 offset:20608
	ds_read_b64_tr_b16 v[192:193], v215 offset:23168
	ds_read_b64_tr_b16 v[194:195], v215 offset:20672
	ds_read_b64_tr_b16 v[196:197], v215 offset:23232
	ds_read_b64_tr_b16 v[198:199], v215 offset:25600
	ds_read_b64_tr_b16 v[200:201], v215 offset:28160
	ds_read_b64_tr_b16 v[202:203], v215 offset:25664
	ds_read_b64_tr_b16 v[204:205], v215 offset:28224
	s_waitcnt lgkmcnt(10)
	v_mfma_f32_32x32x16_bf16 v[0:15], v[182:185], v[96:99], v[0:15]
	ds_read_b64_tr_b16 v[206:207], v215 offset:25728
	ds_read_b64_tr_b16 v[208:209], v215 offset:28288
	s_waitcnt lgkmcnt(10)
	v_mfma_f32_32x32x16_bf16 v[16:31], v[186:189], v[96:99], v[16:31]
	ds_read_b64_tr_b16 v[210:211], v215 offset:25792
	ds_read_b64_tr_b16 v[212:213], v215 offset:28352
	s_waitcnt lgkmcnt(10)
	v_mfma_f32_32x32x16_bf16 v[32:47], v[190:193], v[96:99], v[32:47]
	ds_read_b64_tr_b16 v[182:183], v215 offset:30720
	ds_read_b64_tr_b16 v[184:185], v215 offset:33280
	s_waitcnt lgkmcnt(10)
	v_mfma_f32_32x32x16_bf16 v[48:63], v[194:197], v[96:99], v[48:63]
	s_waitcnt vmcnt(0)
	ds_write_b128 v253, v[160:163] offset:0
	ds_read_b64_tr_b16 v[186:187], v215 offset:30784
	ds_read_b64_tr_b16 v[188:189], v215 offset:33344
	s_waitcnt lgkmcnt(11)
	v_mfma_f32_32x32x16_bf16 v[0:15], v[198:201], v[100:103], v[0:15]
	ds_write_b128 v253, v[164:167] offset:12800
	ds_read_b64_tr_b16 v[190:191], v215 offset:30848
	ds_read_b64_tr_b16 v[192:193], v215 offset:33408
	s_waitcnt lgkmcnt(12)
	v_mfma_f32_32x32x16_bf16 v[16:31], v[202:205], v[100:103], v[16:31]
	ds_write_b128 v254, v[168:171] offset:0
	ds_read_b64_tr_b16 v[194:195], v215 offset:30912
	ds_read_b64_tr_b16 v[196:197], v215 offset:33472
	s_waitcnt lgkmcnt(13)
	v_mfma_f32_32x32x16_bf16 v[32:47], v[206:209], v[100:103], v[32:47]
	ds_write_b128 v218, v[172:175] offset:0
	ds_read_b64_tr_b16 v[198:199], v215 offset:35840
	ds_read_b64_tr_b16 v[200:201], v215 offset:38400
	s_waitcnt lgkmcnt(14)
	v_mfma_f32_32x32x16_bf16 v[48:63], v[210:213], v[100:103], v[48:63]
	ds_write_b128 v218, v[176:179] offset:10240
	ds_read_b64_tr_b16 v[202:203], v215 offset:35904
	ds_read_b64_tr_b16 v[204:205], v215 offset:38464
	s_waitcnt lgkmcnt(15)
	v_mfma_f32_32x32x16_bf16 v[0:15], v[182:185], v[104:107], v[0:15]
	global_load_dwordx4 v[172:175], v222, s[34:35]
	ds_read_b64_tr_b16 v[206:207], v215 offset:35968
	ds_read_b64_tr_b16 v[208:209], v215 offset:38528
	s_waitcnt lgkmcnt(14)
	v_mfma_f32_32x32x16_bf16 v[16:31], v[186:189], v[104:107], v[16:31]
	global_load_dwordx4 v[176:179], v223, s[34:35]
	s_add_u32 s34, s34, 0xe0000
	s_addc_u32 s35, s35, 0
	ds_read_b64_tr_b16 v[210:211], v215 offset:36032
	ds_read_b64_tr_b16 v[212:213], v215 offset:38592
	s_waitcnt lgkmcnt(13)
	v_mfma_f32_32x32x16_bf16 v[32:47], v[190:193], v[104:107], v[32:47]
	global_load_dwordx4 v[160:163], v219, s[30:31]
	s_waitcnt lgkmcnt(10)
	v_mfma_f32_32x32x16_bf16 v[48:63], v[194:197], v[104:107], v[48:63]
	global_load_dwordx4 v[164:167], v220, s[30:31]
	s_add_u32 s30, s30, 0xe0000
	s_addc_u32 s31, s31, 0
	s_waitcnt lgkmcnt(7)
	v_mfma_f32_32x32x16_bf16 v[0:15], v[198:201], v[108:111], v[0:15]
	global_load_dwordx4 v[168:171], v221, s[36:37]
	s_add_u32 s36, s36, 0x22000
	s_addc_u32 s37, s37, 0
	s_waitcnt lgkmcnt(4)
	v_mfma_f32_32x32x16_bf16 v[16:31], v[202:205], v[108:111], v[16:31]
	s_waitcnt lgkmcnt(2)
	v_mfma_f32_32x32x16_bf16 v[32:47], v[206:209], v[108:111], v[32:47]
	s_waitcnt lgkmcnt(0)
	v_mfma_f32_32x32x16_bf16 v[48:63], v[210:213], v[108:111], v[48:63]
	s_branch .Lad_x0_end
; #define LAS __attribute__((address_space(3)))
; DI f32x16 mfma32(bf16x8 a, bf16x8 b, f32x16 c) { return __builtin_amdgcn_mfma_f32_32x32x16_bf16(a, b, c, 0, 0, 0); }
; template <int DQK, int KA8, int DV, bool BIAS, bool JOINT>
; DI void attn_core(LAS unsigned char* lds, const bf16_t* Qrow, const bf16_t* KpA, int ldkA, const bf16_t* KpB, int ldkB, const bf16_t* Vp, int ldv,
;                   int qb, int wid, int lane, const float* qng  , f32x16 (&O)[DV / 32]) {
;     ...
;     auto gload = [&](int kt) {
; #pragma unroll
;         for (int i = 0; i < NL; ++i) { const int c = tid + i * 512;
;             if (i * 512 < NKC) { const int row = c / KC, cc = c % KC;
;                 const bf16_t* src = (cc < KA8) ? KpA + (size_t)(kt * 64 + row) * ldkA + cc * 8 : KpB + (size_t)(kt * 64 + row) * ldkB + (cc - KA8) * 8;
;                 stg[i] = *(const u32x4*)src; }
;             else { const int c2 = c - NKC, row = c2 / VC, cc = c2 % VC; stg[i] = *(const u32x4*)(Vp + (size_t)(kt * 64 + row) * ldv + cc * 8); } }
;     };
;     auto lstore = [&](int buf) {
; #pragma unroll
;         for (int i = 0; i < NL; ++i) { const int c = tid + i * 512;
;             if (i * 512 < NKC) { const int row = c / KC, cc = c % KC; *(LAS u32x4*)(lds + buf * STG + row * KROW + cc * 16) = stg[i]; }
;             else { const int c2 = c - NKC, row = c2 / VC, cc = c2 % VC; *(LAS u32x4*)(lds + buf * STG + 64 * KROW + row * VROW + cc * 16) = stg[i]; } }
;     ...
; #pragma unroll
;             for (int s = 0; s < DQK / 16; ++s) {
;                 const bf16x8 k0 = *(LAS const bf16x8*)(kb + koff + 32 * s), k1 = *(LAS const bf16x8*)(kb + koff + 32 * KROW + 32 * s);
;                 S0 = mfma32(k0, qf[s], S0); S1 = mfma32(k1, qf[s], S1);
;             }
.Lad_x0_qk:
	ds_read_b128 v[182:185], v214 offset:40960
	ds_read_b128 v[186:189], v214 offset:53760
	ds_read_b128 v[190:193], v214 offset:40992
	ds_read_b128 v[194:197], v214 offset:53792
	ds_read_b128 v[198:201], v214 offset:41024
	ds_read_b128 v[202:205], v214 offset:53824
	s_waitcnt lgkmcnt(5)
	v_mfma_f32_32x32x16_bf16 v[64:79], v[182:185], v[112:115], 0
	ds_read_b128 v[206:209], v214 offset:41056
	s_waitcnt lgkmcnt(5)
	v_mfma_f32_32x32x16_bf16 v[80:95], v[186:189], v[112:115], 0
	ds_read_b128 v[210:213], v214 offset:53856
	s_waitcnt lgkmcnt(5)
	v_mfma_f32_32x32x16_bf16 v[64:79], v[190:193], v[116:119], v[64:79]
	ds_read_b128 v[182:185], v214 offset:41088
	s_waitcnt lgkmcnt(5)
	v_mfma_f32_32x32x16_bf16 v[80:95], v[194:197], v[116:119], v[80:95]
	s_waitcnt vmcnt(0)
	ds_write_b128 v253, v[160:163] offset:0
	ds_read_b128 v[186:189], v214 offset:53888
	s_waitcnt lgkmcnt(6)
	v_mfma_f32_32x32x16_bf16 v[64:79], v[198:201], v[120:123], v[64:79]
	ds_write_b128 v253, v[164:167] offset:12800
	ds_read_b128 v[190:193], v214 offset:41120
	s_waitcnt lgkmcnt(7)
	v_mfma_f32_32x32x16_bf16 v[80:95], v[202:205], v[120:123], v[80:95]
	ds_write_b128 v254, v[168:171] offset:0
	ds_read_b128 v[194:197], v214 offset:53920
	s_waitcnt lgkmcnt(8)
	v_mfma_f32_32x32x16_bf16 v[64:79], v[206:209], v[124:127], v[64:79]
	ds_write_b128 v218, v[172:175] offset:0
	ds_read_b128 v[198:201], v214 offset:41152
	s_waitcnt lgkmcnt(9)
	v_mfma_f32_32x32x16_bf16 v[80:95], v[210:213], v[124:127], v[80:95]
	ds_write_b128 v218, v[176:179] offset:10240
	ds_read_b128 v[202:205], v214 offset:53952
	s_waitcnt lgkmcnt(10)
	v_mfma_f32_32x32x16_bf16 v[64:79], v[182:185], v[128:131], v[64:79]
	global_load_dwordx4 v[172:175], v222, s[34:35]
	ds_read_b128 v[206:209], v214 offset:41184
	s_waitcnt lgkmcnt(9)
	v_mfma_f32_32x32x16_bf16 v[80:95], v[186:189], v[128:131], v[80:95]
	global_load_dwordx4 v[176:179], v223, s[34:35]
	s_add_u32 s34, s34, 0xe0000
	s_addc_u32 s35, s35, 0
	ds_read_b128 v[210:213], v214 offset:53984
	s_waitcnt lgkmcnt(8)
	v_mfma_f32_32x32x16_bf16 v[64:79], v[190:193], v[132:135], v[64:79]
	global_load_dwordx4 v[160:163], v219, s[30:31]
	ds_read_b128 v[182:185], v214 offset:41216
	s_waitcnt lgkmcnt(7)
	v_mfma_f32_32x32x16_bf16 v[80:95], v[194:197], v[132:135], v[80:95]
	global_load_dwordx4 v[164:167], v220, s[30:31]
	s_add_u32 s30, s30, 0xe0000
	s_addc_u32 s31, s31, 0
	ds_read_b128 v[186:189], v214 offset:54016
	s_waitcnt lgkmcnt(6)
	v_mfma_f32_32x32x16_bf16 v[64:79], v[198:201], v[136:139], v[64:79]
	global_load_dwordx4 v[168:171], v221, s[36:37]
	s_add_u32 s36, s36, 0x22000
	s_addc_u32 s37, s37, 0
	ds_read_b128 v[190:193], v214 offset:41248
	s_waitcnt lgkmcnt(5)
	v_mfma_f32_32x32x16_bf16 v[80:95], v[202:205], v[136:139], v[80:95]
	ds_read_b128 v[194:197], v214 offset:54048
	s_waitcnt lgkmcnt(5)
	v_mfma_f32_32x32x16_bf16 v[64:79], v[206:209], v[140:143], v[64:79]
	ds_read_b128 v[198:201], v214 offset:41280
	s_waitcnt lgkmcnt(5)
	v_mfma_f32_32x32x16_bf16 v[80:95], v[210:213], v[140:143], v[80:95]
	ds_read_b128 v[202:205], v214 offset:54080
	s_waitcnt lgkmcnt(5)
	v_mfma_f32_32x32x16_bf16 v[64:79], v[182:185], v[144:147], v[64:79]
	ds_read_b128 v[206:209], v214 offset:41312
	s_waitcnt lgkmcnt(5)
	v_mfma_f32_32x32x16_bf16 v[80:95], v[186:189], v[144:147], v[80:95]
	ds_read_b128 v[210:213], v214 offset:54112
	s_waitcnt lgkmcnt(5)
	v_mfma_f32_32x32x16_bf16 v[64:79], v[190:193], v[148:151], v[64:79]
	s_waitcnt lgkmcnt(4)
	v_mfma_f32_32x32x16_bf16 v[80:95], v[194:197], v[148:151], v[80:95]
	s_waitcnt lgkmcnt(3)
	v_mfma_f32_32x32x16_bf16 v[64:79], v[198:201], v[152:155], v[64:79]
	s_waitcnt lgkmcnt(2)
	v_mfma_f32_32x32x16_bf16 v[80:95], v[202:205], v[152:155], v[80:95]
	s_waitcnt lgkmcnt(1)
	v_mfma_f32_32x32x16_bf16 v[64:79], v[206:209], v[156:159], v[64:79]
	s_waitcnt lgkmcnt(0)
	v_mfma_f32_32x32x16_bf16 v[80:95], v[210:213], v[156:159], v[80:95]
	s_branch .Lad_x0_end
.Lad_x0_none:
	s_waitcnt vmcnt(0)
	ds_write_b128 v253, v[160:163] offset:0
	ds_write_b128 v253, v[164:167] offset:12800
	ds_write_b128 v254, v[168:171] offset:0
	ds_write_b128 v218, v[172:175] offset:0
	ds_write_b128 v218, v[176:179] offset:10240
	global_load_dwordx4 v[172:175], v222, s[34:35]
	global_load_dwordx4 v[176:179], v223, s[34:35]
	s_add_u32 s34, s34, 0xe0000
	s_addc_u32 s35, s35, 0
	global_load_dwordx4 v[160:163], v219, s[30:31]
	global_load_dwordx4 v[164:167], v220, s[30:31]
	s_add_u32 s30, s30, 0xe0000
	s_addc_u32 s31, s31, 0
	global_load_dwordx4 v[168:171], v221, s[36:37]
	s_add_u32 s36, s36, 0x22000
	s_addc_u32 s37, s37, 0

; template <int DQK, int KA8, int DV, bool BIAS, bool JOINT>
; DI void attn_core(LAS unsigned char* lds, const bf16_t* Qrow, const bf16_t* KpA, int ldkA, const bf16_t* KpB, int ldkB, const bf16_t* Vp, int ldv,
;                   int qb, int wid, int lane, const float* qng  , f32x16 (&O)[DV / 32]) {
;     ...
;     for (int kt = 0; kt < nkt; ++kt) {
;         if (kt + 1 < nkt) gload(kt + 1);
;         if (JOINT && kt <= myc) {
;             LAS unsigned char* kb = lds + (kt & 1) * STG; LAS unsigned char* vb = kb + 64 * KROW;
;             const bool far = (kt * 64 + 63 - q0w <= -91);
;             f32x16 S0, S1;
; #pragma unroll
;             for (int i = 0; i < 16; ++i) { S0[i] = 0.f; S1[i] = 0.f; }
; #pragma unroll
;             for (int s = 0; s < DQK / 16; ++s) {
;                 const bf16x8 k0 = *(LAS const bf16x8*)(kb + koff + 32 * s), k1 = *(LAS const bf16x8*)(kb + koff + 32 * KROW + 32 * s);
;                 S0 = mfma32(k0, qf[s], S0); S1 = mfma32(k1, qf[s], S1);
;             }
;             if (BIAS && !far) {
;                 const int rb = kt * 64 - (q0w + l32) + 128;
; #pragma unroll
;                 for (int i = 0; i < 16; ++i) { const int i0 = rb + crow(i, hh); S0[i] += btab[i0 < 0 ? 0 : i0]; S1[i] += btab[i0 + 32 < 0 ? 0 : i0 + 32]; }
;             }
;             if (mnz) {
; #pragma unroll
;                 for (int i = 0; i < 16; ++i) { S0[i] -= m; S1[i] -= m; }
;             }
;             float mx = fmaxf(S0[0], S1[0]);
; #pragma unroll
;             for (int i = 1; i < 16; ++i) mx = fmaxf(mx, fmaxf(S0[i], S1[i]));
;             mx = fmaxf(mx, __shfl_xor(mx, 32));
;             if (__any(mx > 64.f || (kt == 0 && mx < -64.f))) {
;                 const float dm = (mx > 64.f || (kt == 0 && mx < -64.f)) ? mx : 0.f, alpha = __builtin_amdgcn_exp2f(-dm); m += dm; mnz = true;
;                 l *= alpha;
; #pragma unroll
;                 for (int dt = 0; dt < DV / 32; ++dt) O[dt] *= alpha;
; #pragma unroll
;                 for (int i = 0; i < 16; ++i) { S0[i] -= dm; S1[i] -= dm; }
;             }
;             float ps = 0.f;
; #pragma unroll
;             for (int i = 0; i < 16; ++i) { S0[i] = __builtin_amdgcn_exp2f(S0[i]); S1[i] = __builtin_amdgcn_exp2f(S1[i]); ps += S0[i] + S1[i]; }
;             l += ps;
; #pragma unroll
;             for (int half = 0; half < 2; ++half)
; #pragma unroll
;                 for (int s = 0; s < 2; ++s) {
.Lad_y0_end:
	s_barrier
	s_add_i32 s59, s24, 1
	s_add_i32 s58, s25, 1
	s_cmp_gt_u32 s59, s58
	s_cbranch_scc1 .Lad_x1_none
	s_cmp_eq_u32 s59, s58
	s_cbranch_scc1 .Lad_x1_pv
	ds_read_b64_tr_b16 v[182:183], v215 offset:0
	ds_read_b64_tr_b16 v[184:185], v215 offset:2560
	ds_read_b64_tr_b16 v[186:187], v215 offset:64
	ds_read_b64_tr_b16 v[188:189], v215 offset:2624
	ds_read_b64_tr_b16 v[190:191], v215 offset:128
	ds_read_b64_tr_b16 v[192:193], v215 offset:2688
	ds_read_b64_tr_b16 v[194:195], v215 offset:192
	ds_read_b64_tr_b16 v[196:197], v215 offset:2752
	ds_read_b64_tr_b16 v[198:199], v215 offset:5120
	ds_read_b64_tr_b16 v[200:201], v215 offset:7680
	ds_read_b64_tr_b16 v[202:203], v215 offset:5184
	ds_read_b64_tr_b16 v[204:205], v215 offset:7744
	s_waitcnt lgkmcnt(10)
	v_mfma_f32_32x32x16_bf16 v[0:15], v[182:185], v[96:99], v[0:15]
	ds_read_b64_tr_b16 v[206:207], v215 offset:5248
	ds_read_b64_tr_b16 v[208:209], v215 offset:7808
	s_waitcnt lgkmcnt(10)
	v_mfma_f32_32x32x16_bf16 v[16:31], v[186:189], v[96:99], v[16:31]
	ds_read_b64_tr_b16 v[210:211], v215 offset:5312
	ds_read_b64_tr_b16 v[212:213], v215 offset:7872
	s_waitcnt lgkmcnt(10)
	v_mfma_f32_32x32x16_bf16 v[32:47], v[190:193], v[96:99], v[32:47]
	ds_read_b64_tr_b16 v[182:183], v215 offset:10240
	ds_read_b64_tr_b16 v[184:185], v215 offset:12800
	s_waitcnt lgkmcnt(10)
	v_mfma_f32_32x32x16_bf16 v[48:63], v[194:197], v[96:99], v[48:63]
	s_waitcnt vmcnt(0)
	ds_write_b128 v216, v[160:163] offset:40960
	ds_read_b64_tr_b16 v[186:187], v215 offset:10304
	ds_read_b64_tr_b16 v[188:189], v215 offset:12864
	s_waitcnt lgkmcnt(11)
	v_mfma_f32_32x32x16_bf16 v[0:15], v[198:201], v[100:103], v[0:15]
	ds_write_b128 v216, v[164:167] offset:53760
	ds_read_b64_tr_b16 v[190:191], v215 offset:10368
	ds_read_b64_tr_b16 v[192:193], v215 offset:12928
	s_waitcnt lgkmcnt(12)
	v_mfma_f32_32x32x16_bf16 v[16:31], v[202:205], v[100:103], v[16:31]
	ds_write_b128 v217, v[168:171] offset:40960
	ds_read_b64_tr_b16 v[194:195], v215 offset:10432
	ds_read_b64_tr_b16 v[196:197], v215 offset:12992
	s_waitcnt lgkmcnt(13)
	v_mfma_f32_32x32x16_bf16 v[32:47], v[206:209], v[100:103], v[32:47]
	ds_write_b128 v218, v[172:175] offset:20480
	ds_read_b64_tr_b16 v[198:199], v215 offset:15360
	ds_read_b64_tr_b16 v[200:201], v215 offset:17920
	s_waitcnt lgkmcnt(14)
	v_mfma_f32_32x32x16_bf16 v[48:63], v[210:213], v[100:103], v[48:63]
	ds_write_b128 v218, v[176:179] offset:30720
	ds_read_b64_tr_b16 v[202:203], v215 offset:15424
	ds_read_b64_tr_b16 v[204:205], v215 offset:17984
	s_waitcnt lgkmcnt(15)
	v_mfma_f32_32x32x16_bf16 v[0:15], v[182:185], v[104:107], v[0:15]
	global_load_dwordx4 v[172:175], v222, s[34:35]
	ds_read_b64_tr_b16 v[206:207], v215 offset:15488
	ds_read_b64_tr_b16 v[208:209], v215 offset:18048
	s_waitcnt lgkmcnt(14)
	v_mfma_f32_32x32x16_bf16 v[16:31], v[186:189], v[104:107], v[16:31]
	global_load_dwordx4 v[176:179], v223, s[34:35]
	s_add_u32 s34, s34, 0xe0000
	s_addc_u32 s35, s35, 0
	ds_read_b64_tr_b16 v[210:211], v215 offset:15552
	ds_read_b64_tr_b16 v[212:213], v215 offset:18112
	s_waitcnt lgkmcnt(13)
	v_mfma_f32_32x32x16_bf16 v[32:47], v[190:193], v[104:107], v[32:47]
	global_load_dwordx4 v[160:163], v219, s[30:31]
	ds_read_b128 v[182:185], v252 offset:0
	s_waitcnt lgkmcnt(11)
	v_mfma_f32_32x32x16_bf16 v[48:63], v[194:197], v[104:107], v[48:63]
	global_load_dwordx4 v[164:167], v220, s[30:31]
	s_add_u32 s30, s30, 0xe0000
	s_addc_u32 s31, s31, 0
	ds_read_b128 v[186:189], v252 offset:12800
	s_waitcnt lgkmcnt(9)
	v_mfma_f32_32x32x16_bf16 v[0:15], v[198:201], v[108:111], v[0:15]
	global_load_dwordx4 v[168:171], v221, s[36:37]
	s_add_u32 s36, s36, 0x22000
	s_addc_u32 s37, s37, 0
	ds_read_b128 v[190:193], v252 offset:32
	s_waitcnt lgkmcnt(7)
	v_mfma_f32_32x32x16_bf16 v[16:31], v[202:205], v[108:111], v[16:31]
	ds_read_b128 v[194:197], v252 offset:12832
	s_waitcnt lgkmcnt(6)
	v_mfma_f32_32x32x16_bf16 v[32:47], v[206:209], v[108:111], v[32:47]
	ds_read_b128 v[198:201], v252 offset:64
	s_waitcnt lgkmcnt(5)
	v_mfma_f32_32x32x16_bf16 v[48:63], v[210:213], v[108:111], v[48:63]
	ds_read_b128 v[202:205], v252 offset:12864
	s_waitcnt lgkmcnt(5)
	v_mfma_f32_32x32x16_bf16 v[64:79], v[182:185], v[112:115], 0
	ds_read_b128 v[206:209], v252 offset:96
	s_waitcnt lgkmcnt(5)
	v_mfma_f32_32x32x16_bf16 v[80:95], v[186:189], v[112:115], 0
	ds_read_b128 v[210:213], v252 offset:12896
	s_waitcnt lgkmcnt(5)
	v_mfma_f32_32x32x16_bf16 v[64:79], v[190:193], v[116:119], v[64:79]
	ds_read_b128 v[182:185], v252 offset:128
	s_waitcnt lgkmcnt(5)
	v_mfma_f32_32x32x16_bf16 v[80:95], v[194:197], v[116:119], v[80:95]
	ds_read_b128 v[186:189], v252 offset:12928
	s_waitcnt lgkmcnt(5)
	v_mfma_f32_32x32x16_bf16 v[64:79], v[198:201], v[120:123], v[64:79]
	ds_read_b128 v[190:193], v252 offset:160
	s_waitcnt lgkmcnt(5)
	v_mfma_f32_32x32x16_bf16 v[80:95], v[202:205], v[120:123], v[80:95]
	ds_read_b128 v[194:197], v252 offset:12960
	s_waitcnt lgkmcnt(5)
	v_mfma_f32_32x32x16_bf16 v[64:79], v[206:209], v[124:127], v[64:79]
	ds_read_b128 v[198:201], v252 offset:192
	s_waitcnt lgkmcnt(5)
	v_mfma_f32_32x32x16_bf16 v[80:95], v[210:213], v[124:127], v[80:95]
	ds_read_b128 v[202:205], v252 offset:12992
	s_waitcnt lgkmcnt(5)
	v_mfma_f32_32x32x16_bf16 v[64:79], v[182:185], v[128:131], v[64:79]
	ds_read_b128 v[206:209], v252 offset:224
	s_waitcnt lgkmcnt(5)
	v_mfma_f32_32x32x16_bf16 v[80:95], v[186:189], v[128:131], v[80:95]
	ds_read_b128 v[210:213], v252 offset:13024
	s_waitcnt lgkmcnt(5)
	v_mfma_f32_32x32x16_bf16 v[64:79], v[190:193], v[132:135], v[64:79]
	ds_read_b128 v[182:185], v252 offset:256
	s_waitcnt lgkmcnt(5)
; template <int DQK, int KA8, int DV, bool BIAS, bool JOINT>
; DI void attn_core(LAS unsigned char* lds, const bf16_t* Qrow, const bf16_t* KpA, int ldkA, const bf16_t* KpB, int ldkB, const bf16_t* Vp, int ldv,
;                   int qb, int wid, int lane, const float* qng  , f32x16 (&O)[DV / 32]) {
;     ...
;     for (int kt = 0; kt < nkt; ++kt) {
;         if (kt + 1 < nkt) gload(kt + 1);
;         if (JOINT && kt <= myc) {
;             LAS unsigned char* kb = lds + (kt & 1) * STG; LAS unsigned char* vb = kb + 64 * KROW;
;             const bool far = (kt * 64 + 63 - q0w <= -91);
;             f32x16 S0, S1;
; #pragma unroll
;             for (int i = 0; i < 16; ++i) { S0[i] = 0.f; S1[i] = 0.f; }
; #pragma unroll
;             for (int s = 0; s < DQK / 16; ++s) {
;                 const bf16x8 k0 = *(LAS const bf16x8*)(kb + koff + 32 * s), k1 = *(LAS const bf16x8*)(kb + koff + 32 * KROW + 32 * s);
;                 S0 = mfma32(k0, qf[s], S0); S1 = mfma32(k1, qf[s], S1);
;             }
;             if (BIAS && !far) {
;                 const int rb = kt * 64 - (q0w + l32) + 128;
; #pragma unroll
;                 for (int i = 0; i < 16; ++i) { const int i0 = rb + crow(i, hh); S0[i] += btab[i0 < 0 ? 0 : i0]; S1[i] += btab[i0 + 32 < 0 ? 0 : i0 + 32]; }
;             }
;             if (mnz) {
; #pragma unroll
;                 for (int i = 0; i < 16; ++i) { S0[i] -= m; S1[i] -= m; }
;             }
;             float mx = fmaxf(S0[0], S1[0]);
; #pragma unroll
;             for (int i = 1; i < 16; ++i) mx = fmaxf(mx, fmaxf(S0[i], S1[i]));
;             mx = fmaxf(mx, __shfl_xor(mx, 32));
;             if (__any(mx > 64.f || (kt == 0 && mx < -64.f))) {
;                 const float dm = (mx > 64.f || (kt == 0 && mx < -64.f)) ? mx : 0.f, alpha = __builtin_amdgcn_exp2f(-dm); m += dm; mnz = true;
;                 l *= alpha;
; #pragma unroll
;                 for (int dt = 0; dt < DV / 32; ++dt) O[dt] *= alpha;
; #pragma unroll
;                 for (int i = 0; i < 16; ++i) { S0[i] -= dm; S1[i] -= dm; }
;             }
;             float ps = 0.f;
; #pragma unroll
;             for (int i = 0; i < 16; ++i) { S0[i] = __builtin_amdgcn_exp2f(S0[i]); S1[i] = __builtin_amdgcn_exp2f(S1[i]); ps += S0[i] + S1[i]; }
;             l += ps;
; #pragma unroll
;             for (int half = 0; half < 2; ++half)
; #pragma unroll
;                 for (int s = 0; s < 2; ++s) {
	v_mfma_f32_32x32x16_bf16 v[80:95], v[194:197], v[132:135], v[80:95]
	ds_read_b128 v[186:189], v252 offset:13056
	s_waitcnt lgkmcnt(5)
	v_mfma_f32_32x32x16_bf16 v[64:79], v[198:201], v[136:139], v[64:79]
	ds_read_b128 v[190:193], v252 offset:288
	s_waitcnt lgkmcnt(5)
	v_mfma_f32_32x32x16_bf16 v[80:95], v[202:205], v[136:139], v[80:95]
	ds_read_b128 v[194:197], v252 offset:13088
	s_waitcnt lgkmcnt(5)
	v_mfma_f32_32x32x16_bf16 v[64:79], v[206:209], v[140:143], v[64:79]
	ds_read_b128 v[198:201], v252 offset:320
	s_waitcnt lgkmcnt(5)
	v_mfma_f32_32x32x16_bf16 v[80:95], v[210:213], v[140:143], v[80:95]
	ds_read_b128 v[202:205], v252 offset:13120
	s_waitcnt lgkmcnt(5)
	v_mfma_f32_32x32x16_bf16 v[64:79], v[182:185], v[144:147], v[64:79]
	ds_read_b128 v[206:209], v252 offset:352
	s_waitcnt lgkmcnt(5)
	v_mfma_f32_32x32x16_bf16 v[80:95], v[186:189], v[144:147], v[80:95]
	ds_read_b128 v[210:213], v252 offset:13152
	s_waitcnt lgkmcnt(5)
	v_mfma_f32_32x32x16_bf16 v[64:79], v[190:193], v[148:151], v[64:79]
	s_waitcnt lgkmcnt(4)
	v_mfma_f32_32x32x16_bf16 v[80:95], v[194:197], v[148:151], v[80:95]
	s_waitcnt lgkmcnt(3)
	v_mfma_f32_32x32x16_bf16 v[64:79], v[198:201], v[152:155], v[64:79]
	s_waitcnt lgkmcnt(2)
	v_mfma_f32_32x32x16_bf16 v[80:95], v[202:205], v[152:155], v[80:95]
	s_waitcnt lgkmcnt(1)
	v_mfma_f32_32x32x16_bf16 v[64:79], v[206:209], v[156:159], v[64:79]
	s_waitcnt lgkmcnt(0)
	v_mfma_f32_32x32x16_bf16 v[80:95], v[210:213], v[156:159], v[80:95]
	s_branch .Lad_x1_end
.Lad_x1_pv:
	ds_read_b64_tr_b16 v[182:183], v215 offset:0
	ds_read_b64_tr_b16 v[184:185], v215 offset:2560
	ds_read_b64_tr_b16 v[186:187], v215 offset:64
	ds_read_b64_tr_b16 v[188:189], v215 offset:2624
	ds_read_b64_tr_b16 v[190:191], v215 offset:128
	ds_read_b64_tr_b16 v[192:193], v215 offset:2688
	ds_read_b64_tr_b16 v[194:195], v215 offset:192
	ds_read_b64_tr_b16 v[196:197], v215 offset:2752
	ds_read_b64_tr_b16 v[198:199], v215 offset:5120
	ds_read_b64_tr_b16 v[200:201], v215 offset:7680
	ds_read_b64_tr_b16 v[202:203], v215 offset:5184
	ds_read_b64_tr_b16 v[204:205], v215 offset:7744
	s_waitcnt lgkmcnt(10)
	v_mfma_f32_32x32x16_bf16 v[0:15], v[182:185], v[96:99], v[0:15]
	ds_read_b64_tr_b16 v[206:207], v215 offset:5248
	ds_read_b64_tr_b16 v[208:209], v215 offset:7808
	s_waitcnt lgkmcnt(10)
	v_mfma_f32_32x32x16_bf16 v[16:31], v[186:189], v[96:99], v[16:31]
	ds_read_b64_tr_b16 v[210:211], v215 offset:5312
	ds_read_b64_tr_b16 v[212:213], v215 offset:7872
	s_waitcnt lgkmcnt(10)
	v_mfma_f32_32x32x16_bf16 v[32:47], v[190:193], v[96:99], v[32:47]
	ds_read_b64_tr_b16 v[182:183], v215 offset:10240
	ds_read_b64_tr_b16 v[184:185], v215 offset:12800
	s_waitcnt lgkmcnt(10)
	v_mfma_f32_32x32x16_bf16 v[48:63], v[194:197], v[96:99], v[48:63]
	s_waitcnt vmcnt(0)
	ds_write_b128 v216, v[160:163] offset:40960
	ds_read_b64_tr_b16 v[186:187], v215 offset:10304
	ds_read_b64_tr_b16 v[188:189], v215 offset:12864
	s_waitcnt lgkmcnt(11)
	v_mfma_f32_32x32x16_bf16 v[0:15], v[198:201], v[100:103], v[0:15]
	ds_write_b128 v216, v[164:167] offset:53760
	ds_read_b64_tr_b16 v[190:191], v215 offset:10368
	ds_read_b64_tr_b16 v[192:193], v215 offset:12928
	s_waitcnt lgkmcnt(12)
	v_mfma_f32_32x32x16_bf16 v[16:31], v[202:205], v[100:103], v[16:31]
	ds_write_b128 v217, v[168:171] offset:40960
	ds_read_b64_tr_b16 v[194:195], v215 offset:10432
	ds_read_b64_tr_b16 v[196:197], v215 offset:12992
	s_waitcnt lgkmcnt(13)
	v_mfma_f32_32x32x16_bf16 v[32:47], v[206:209], v[100:103], v[32:47]
	ds_write_b128 v218, v[172:175] offset:20480
	ds_read_b64_tr_b16 v[198:199], v215 offset:15360
	ds_read_b64_tr_b16 v[200:201], v215 offset:17920
	s_waitcnt lgkmcnt(14)
	v_mfma_f32_32x32x16_bf16 v[48:63], v[210:213], v[100:103], v[48:63]
	ds_write_b128 v218, v[176:179] offset:30720
	ds_read_b64_tr_b16 v[202:203], v215 offset:15424
	ds_read_b64_tr_b16 v[204:205], v215 offset:17984
	s_waitcnt lgkmcnt(15)
	v_mfma_f32_32x32x16_bf16 v[0:15], v[182:185], v[104:107], v[0:15]
	global_load_dwordx4 v[172:175], v222, s[34:35]
	ds_read_b64_tr_b16 v[206:207], v215 offset:15488
	ds_read_b64_tr_b16 v[208:209], v215 offset:18048
	s_waitcnt lgkmcnt(14)
	v_mfma_f32_32x32x16_bf16 v[16:31], v[186:189], v[104:107], v[16:31]
	global_load_dwordx4 v[176:179], v223, s[34:35]
	s_add_u32 s34, s34, 0xe0000
	s_addc_u32 s35, s35, 0
	ds_read_b64_tr_b16 v[210:211], v215 offset:15552
	ds_read_b64_tr_b16 v[212:213], v215 offset:18112
	s_waitcnt lgkmcnt(13)
	v_mfma_f32_32x32x16_bf16 v[32:47], v[190:193], v[104:107], v[32:47]
	global_load_dwordx4 v[160:163], v219, s[30:31]
	s_waitcnt lgkmcnt(10)
	v_mfma_f32_32x32x16_bf16 v[48:63], v[194:197], v[104:107], v[48:63]
	global_load_dwordx4 v[164:167], v220, s[30:31]
	s_add_u32 s30, s30, 0xe0000
	s_addc_u32 s31, s31, 0
	s_waitcnt lgkmcnt(7)
	v_mfma_f32_32x32x16_bf16 v[0:15], v[198:201], v[108:111], v[0:15]
	global_load_dwordx4 v[168:171], v221, s[36:37]
	s_add_u32 s36, s36, 0x22000
	s_addc_u32 s37, s37, 0
	s_waitcnt lgkmcnt(4)
	v_mfma_f32_32x32x16_bf16 v[16:31], v[202:205], v[108:111], v[16:31]
	s_waitcnt lgkmcnt(2)
	v_mfma_f32_32x32x16_bf16 v[32:47], v[206:209], v[108:111], v[32:47]
	s_waitcnt lgkmcnt(0)
	v_mfma_f32_32x32x16_bf16 v[48:63], v[210:213], v[108:111], v[48:63]
	s_branch .Lad_x1_end
.Lad_x1_none:
	s_waitcnt vmcnt(0)
	ds_write_b128 v216, v[160:163] offset:40960
	ds_write_b128 v216, v[164:167] offset:53760
	ds_write_b128 v217, v[168:171] offset:40960
	ds_write_b128 v218, v[172:175] offset:20480
	ds_write_b128 v218, v[176:179] offset:30720
	global_load_dwordx4 v[172:175], v222, s[34:35]
	global_load_dwordx4 v[176:179], v223, s[34:35]
	s_add_u32 s34, s34, 0xe0000
	s_addc_u32 s35, s35, 0
	global_load_dwordx4 v[160:163], v219, s[30:31]
	global_load_dwordx4 v[164:167], v220, s[30:31]
	s_add_u32 s30, s30, 0xe0000
	s_addc_u32 s31, s31, 0
	global_load_dwordx4 v[168:171], v221, s[36:37]
	s_add_u32 s36, s36, 0x22000
	s_addc_u32 s37, s37, 0
